# GEMM K-loops: SGPR-base prefetch loads (wave-uniform base + 32-bit lane offsets) replace 64-bit VALU address chains; same numerics
# speedup vs baseline: 1.0374x; 1.0049x over previous
.LBB0_204:
	s_and_b32 s2, s7, 7
	s_lshl_b32 s16, s2, 8
	s_and_b32 s2, s14, 7
	v_readlane_b32 s3, v253, 25
	s_or_b32 s2, s2, s3
	s_mul_hi_i32 s3, s14, 0x2aaaaaab
	s_lshr_b32 s4, s3, 31
	s_lshr_b32 s3, s3, 4
	s_add_i32 s3, s3, s4
	s_lshl_b32 s4, s2, 8
	s_ashr_i32 s2, s14, 3
	s_lshl_b32 s17, s3, 11
	s_mul_hi_i32 s3, s2, 0x2aaaaaab
	s_lshr_b32 s5, s3, 31
	s_lshr_b32 s3, s3, 1
	s_add_i32 s3, s3, s5
	s_mul_i32 s3, s3, 12
	s_sub_i32 s2, s2, s3
	s_add_i32 s4, s4, s17
	s_lshl_b32 s5, s2, 8
	s_cmp_ge_i32 s5, s6
	s_mov_b64 s[2:3], -1
	s_cbranch_scc0 .LBB0_212
	v_mov_b32_e32 v188, v234
	v_readlane_b32 s2, v255, 23
	v_ashrrev_i32_e32 v50, 3, v188
	v_add_u32_e32 v0, s4, v50
	v_ashrrev_i32_e32 v1, 31, v0
	v_lshlrev_b64 v[0:1], 11, v[0:1]
	v_add_u32_e32 v2, s5, v50
	v_lshlrev_b32_e32 v189, 4, v188
	v_ashrrev_i32_e32 v3, 31, v2
	v_and_b32_e32 v200, 0x70, v189
	v_lshl_add_u64 v[0:1], s[20:21], 0, v[0:1]
	v_lshlrev_b64 v[32:33], 11, v[2:3]
	v_readlane_b32 s3, v255, 24
	v_lshl_add_u64 v[34:35], v[0:1], 0, v[200:201]
	v_add_co_u32_e32 v38, vcc, s25, v34
	v_lshl_add_u64 v[2:3], s[2:3], 0, v[32:33]
	v_lshl_add_u64 v[36:37], v[2:3], 0, v[200:201]
	v_addc_co_u32_e32 v39, vcc, 0, v35, vcc
	v_add_co_u32_e32 v40, vcc, s25, v36
	s_mov_b32 s2, 0x60000
	s_nop 0
	v_addc_co_u32_e32 v41, vcc, 0, v37, vcc
	v_add_co_u32_e32 v42, vcc, s47, v34
	global_load_dwordx4 v[0:3], v[34:35], off
	global_load_dwordx4 v[4:7], v[36:37], off
	v_addc_co_u32_e32 v43, vcc, 0, v35, vcc
	v_add_co_u32_e32 v44, vcc, s47, v36
	global_load_dwordx4 v[8:11], v[38:39], off
	global_load_dwordx4 v[12:15], v[40:41], off
	v_addc_co_u32_e32 v45, vcc, 0, v37, vcc
	v_add_co_u32_e32 v46, vcc, s2, v34
	global_load_dwordx4 v[16:19], v[42:43], off
	global_load_dwordx4 v[20:23], v[44:45], off
	v_addc_co_u32_e32 v47, vcc, 0, v35, vcc
	v_add_co_u32_e32 v48, vcc, s2, v36
	v_mul_lo_u32 v51, v50, s24
	s_nop 0
	v_addc_co_u32_e32 v49, vcc, 0, v37, vcc
	global_load_dwordx4 v[24:27], v[46:47], off
	global_load_dwordx4 v[28:31], v[48:49], off
	v_add3_u32 v193, v51, v200, 0
	s_add_i32 s2, s16, s17
	s_add_i32 s2, s2, s0
	v_readfirstlane_b32 s3, v188
	s_ashr_i32 s35, s3, 6
	v_add_u32_e32 v50, s2, v50
	s_ashr_i32 s22, s3, 1
	s_lshl_b32 s2, s35, 7
	v_ashrrev_i32_e32 v51, 31, v50
	v_and_b32_e32 v190, 31, v188
	s_andn2_b32 s22, s22, 63
	s_and_b32 s36, s2, 0x80
	v_lshlrev_b64 v[50:51], 11, v[50:51]
	v_bfe_u32 v191, v188, 5, 1
	v_or_b32_e32 v52, s22, v190
	v_or_b32_e32 v53, s36, v190
	v_or_b32_e32 v32, v32, v200
	v_or_b32_e32 v50, v50, v200
	s_mov_b32 s1, 0x60000
	s_mov_b32 s34, 0
	v_lshlrev_b32_e32 v192, 4, v191
	v_mul_lo_u32 v194, v52, s24
	v_mul_u32_u24_e32 v195, 0x90, v53
	v_lshl_add_u64 v[184:185], s[30:31], 0, v[32:33]
	v_lshl_add_u64 v[186:187], s[10:11], 0, v[50:51]
	s_mov_b64 s[2:3], 0
	s_mov_b32 s37, 2
	s_waitcnt vmcnt(7)
	ds_write_b128 v193, v[0:3]
	s_waitcnt vmcnt(6)
	ds_write_b128 v193, v[4:7] offset:36864
	s_waitcnt vmcnt(5)
	ds_write_b128 v193, v[8:11] offset:9216
	s_waitcnt vmcnt(4)
	ds_write_b128 v193, v[12:15] offset:46080
	s_waitcnt vmcnt(3)
	ds_write_b128 v193, v[16:19] offset:18432
	s_waitcnt vmcnt(2)
	ds_write_b128 v193, v[20:23] offset:55296
	s_waitcnt vmcnt(1)
	ds_write_b128 v193, v[24:27] offset:27648
	s_waitcnt vmcnt(0)
	ds_write_b128 v193, v[28:31] offset:64512
	s_waitcnt lgkmcnt(0)
	s_barrier
	global_load_dwordx4 v[128:131], v[34:35], off offset:128
	global_load_dwordx4 v[132:135], v[36:37], off offset:128
	global_load_dwordx4 v[136:139], v[38:39], off offset:128
	global_load_dwordx4 v[140:143], v[40:41], off offset:128
	global_load_dwordx4 v[144:147], v[42:43], off offset:128
	global_load_dwordx4 v[148:151], v[44:45], off offset:128
	global_load_dwordx4 v[152:155], v[46:47], off offset:128
	global_load_dwordx4 v[156:159], v[48:49], off offset:128
	v_mov_b32_e32 v0, 0
	v_mov_b32_e32 v1, v0
	v_mov_b32_e32 v2, v0
	v_mov_b32_e32 v3, v0
	v_mov_b32_e32 v4, v0
	v_mov_b32_e32 v5, v0
	v_mov_b32_e32 v6, v0
	v_mov_b32_e32 v7, v0
	v_mov_b32_e32 v8, v0
	v_mov_b32_e32 v9, v0
	v_mov_b32_e32 v10, v0
	v_mov_b32_e32 v11, v0
	v_mov_b32_e32 v12, v0
	v_mov_b32_e32 v13, v0
	v_mov_b32_e32 v14, v0
	v_mov_b32_e32 v15, v0
	v_mov_b32_e32 v32, v0
	v_mov_b32_e32 v33, v0
	v_mov_b32_e32 v34, v0
	v_mov_b32_e32 v35, v0
	v_mov_b32_e32 v36, v0
	v_mov_b32_e32 v37, v0
	v_mov_b32_e32 v38, v0
	v_mov_b32_e32 v39, v0
	v_mov_b32_e32 v40, v0
	v_mov_b32_e32 v41, v0
	v_mov_b32_e32 v42, v0
	v_mov_b32_e32 v43, v0
	v_mov_b32_e32 v44, v0
	v_mov_b32_e32 v45, v0
	v_mov_b32_e32 v46, v0
	v_mov_b32_e32 v47, v0
	v_mov_b32_e32 v64, v0
	v_mov_b32_e32 v65, v0
	v_mov_b32_e32 v66, v0
	v_mov_b32_e32 v67, v0
	v_mov_b32_e32 v68, v0
	v_mov_b32_e32 v69, v0
	v_mov_b32_e32 v70, v0
	v_mov_b32_e32 v71, v0
	v_mov_b32_e32 v72, v0
	v_mov_b32_e32 v73, v0
	v_mov_b32_e32 v74, v0
	v_mov_b32_e32 v75, v0
	v_mov_b32_e32 v76, v0
	v_mov_b32_e32 v77, v0
	v_mov_b32_e32 v78, v0
	v_mov_b32_e32 v79, v0
	v_mov_b32_e32 v96, v0
	v_mov_b32_e32 v97, v0
	v_mov_b32_e32 v98, v0
	v_mov_b32_e32 v99, v0
	v_mov_b32_e32 v100, v0
	v_mov_b32_e32 v101, v0
	v_mov_b32_e32 v102, v0
	v_mov_b32_e32 v103, v0
	v_mov_b32_e32 v104, v0
	v_mov_b32_e32 v105, v0
	v_mov_b32_e32 v106, v0
	v_mov_b32_e32 v107, v0
	v_mov_b32_e32 v108, v0
	v_mov_b32_e32 v109, v0
	v_mov_b32_e32 v110, v0
	v_mov_b32_e32 v111, v0
	v_mov_b32_e32 v16, v0
	v_mov_b32_e32 v17, v0
	v_mov_b32_e32 v18, v0
	v_mov_b32_e32 v19, v0
	v_mov_b32_e32 v20, v0
	v_mov_b32_e32 v21, v0
	v_mov_b32_e32 v22, v0
	v_mov_b32_e32 v23, v0
	v_mov_b32_e32 v24, v0
	v_mov_b32_e32 v25, v0
	v_mov_b32_e32 v26, v0
	v_mov_b32_e32 v27, v0
	v_mov_b32_e32 v28, v0
	v_mov_b32_e32 v29, v0
	v_mov_b32_e32 v30, v0
	v_mov_b32_e32 v31, v0
	v_mov_b32_e32 v48, v0
	v_mov_b32_e32 v49, v0
	v_mov_b32_e32 v50, v0
	v_mov_b32_e32 v51, v0
	v_mov_b32_e32 v52, v0
	v_mov_b32_e32 v53, v0
	v_mov_b32_e32 v54, v0
	v_mov_b32_e32 v55, v0
	v_mov_b32_e32 v56, v0
	v_mov_b32_e32 v57, v0
	v_mov_b32_e32 v58, v0
	v_mov_b32_e32 v59, v0
	v_mov_b32_e32 v60, v0
	v_mov_b32_e32 v61, v0
	v_mov_b32_e32 v62, v0
	v_mov_b32_e32 v63, v0
	v_mov_b32_e32 v80, v0
	v_mov_b32_e32 v81, v0
	v_mov_b32_e32 v82, v0
	v_mov_b32_e32 v83, v0
	v_mov_b32_e32 v84, v0
	v_mov_b32_e32 v85, v0
	v_mov_b32_e32 v86, v0
	v_mov_b32_e32 v87, v0
	v_mov_b32_e32 v88, v0
	v_mov_b32_e32 v89, v0
	v_mov_b32_e32 v90, v0
	v_mov_b32_e32 v91, v0
	v_mov_b32_e32 v92, v0
	v_mov_b32_e32 v93, v0
	v_mov_b32_e32 v94, v0
	v_mov_b32_e32 v95, v0
	v_mov_b32_e32 v112, v0
	v_mov_b32_e32 v113, v0
	v_mov_b32_e32 v114, v0
	v_mov_b32_e32 v115, v0
	v_mov_b32_e32 v116, v0
	v_mov_b32_e32 v117, v0
	v_mov_b32_e32 v118, v0
	v_mov_b32_e32 v119, v0
	v_mov_b32_e32 v120, v0
	v_mov_b32_e32 v121, v0
	v_mov_b32_e32 v122, v0
	v_mov_b32_e32 v123, v0
	v_mov_b32_e32 v124, v0
	v_mov_b32_e32 v125, v0
	v_mov_b32_e32 v126, v0
	v_mov_b32_e32 v127, v0
	v_readfirstlane_b32 s92, v186
	v_readfirstlane_b32 s93, v187
	v_readfirstlane_b32 s94, v184
	v_readfirstlane_b32 s95, v185
	s_nop 1
	v_subrev_u32_e32 v248, s92, v186
	v_add_u32_e32 v249, 0x20000, v248
	v_add_u32_e32 v250, 0x40000, v248
	v_add_u32_e32 v251, 0x60000, v248
	s_add_u32 s92, s92, 0x16d00000
	s_addc_u32 s93, s93, 0
	s_add_u32 s94, s94, 0x100000
	s_addc_u32 s95, s95, 0
	s_branch .LBB0_208

.LBB0_208:
	s_add_i32 s12, s37, -2
	s_and_b32 s12, s12, 2
	s_mul_i32 s12, s12, 0x9000
	s_add_i32 s12, s12, 0
	v_add3_u32 v200, s12, v195, v192
	ds_read_b128 v[160:163], v200
	ds_read_b128 v[168:171], v200 offset:4608
	ds_read_b128 v[172:175], v200 offset:9216
	ds_read_b128 v[176:179], v200 offset:13824
	v_add3_u32 v214, s12, v194, v192
	ds_read_b128 v[164:167], v214 offset:36864
	s_cmpk_eq_i32 s2, 0x780
	s_waitcnt lgkmcnt(0)
	v_mfma_f32_32x32x16_bf16 v[112:127], v[160:163], v[164:167], v[112:127]
	v_mfma_f32_32x32x16_bf16 v[80:95], v[168:171], v[164:167], v[80:95]
	v_mfma_f32_32x32x16_bf16 v[48:63], v[172:175], v[164:167], v[48:63]
	v_mfma_f32_32x32x16_bf16 v[16:31], v[176:179], v[164:167], v[16:31]
	ds_read_b128 v[164:167], v214 offset:41472
	s_waitcnt lgkmcnt(0)
	v_mfma_f32_32x32x16_bf16 v[96:111], v[160:163], v[164:167], v[96:111]
	v_mfma_f32_32x32x16_bf16 v[64:79], v[168:171], v[164:167], v[64:79]
	v_mfma_f32_32x32x16_bf16 v[32:47], v[172:175], v[164:167], v[32:47]
	ds_read_b128 v[160:163], v214 offset:36896
	ds_read_b128 v[168:171], v200 offset:32
	ds_read_b128 v[172:175], v200 offset:4640
	ds_read_b128 v[180:183], v200 offset:9248
	ds_read_b128 v[196:199], v200 offset:13856
	ds_read_b128 v[202:205], v214 offset:41504
	v_mfma_f32_32x32x16_bf16 v[0:15], v[176:179], v[164:167], v[0:15]
	s_waitcnt lgkmcnt(4)
	v_mfma_f32_32x32x16_bf16 v[112:127], v[168:171], v[160:163], v[112:127]
	s_waitcnt lgkmcnt(3)
	v_mfma_f32_32x32x16_bf16 v[80:95], v[172:175], v[160:163], v[80:95]
	s_waitcnt lgkmcnt(2)
	v_mfma_f32_32x32x16_bf16 v[48:63], v[180:183], v[160:163], v[48:63]
	s_waitcnt lgkmcnt(1)
	v_mfma_f32_32x32x16_bf16 v[16:31], v[196:199], v[160:163], v[16:31]
	s_waitcnt lgkmcnt(0)
	v_mfma_f32_32x32x16_bf16 v[96:111], v[168:171], v[202:205], v[96:111]
	v_mfma_f32_32x32x16_bf16 v[64:79], v[172:175], v[202:205], v[64:79]
	ds_read_b128 v[160:163], v214 offset:36928
	ds_read_b128 v[206:209], v214 offset:41536
	ds_read_b128 v[164:167], v200 offset:64
	ds_read_b128 v[168:171], v200 offset:4672
	ds_read_b128 v[172:175], v200 offset:9280
	ds_read_b128 v[210:213], v200 offset:13888
	v_mfma_f32_32x32x16_bf16 v[32:47], v[180:183], v[202:205], v[32:47]
	v_mfma_f32_32x32x16_bf16 v[0:15], v[196:199], v[202:205], v[0:15]
	s_waitcnt lgkmcnt(3)
	v_mfma_f32_32x32x16_bf16 v[112:127], v[164:167], v[160:163], v[112:127]
	s_waitcnt lgkmcnt(2)
	v_mfma_f32_32x32x16_bf16 v[80:95], v[168:171], v[160:163], v[80:95]
	s_waitcnt lgkmcnt(1)
	v_mfma_f32_32x32x16_bf16 v[48:63], v[172:175], v[160:163], v[48:63]
	s_waitcnt lgkmcnt(0)
	v_mfma_f32_32x32x16_bf16 v[16:31], v[210:213], v[160:163], v[16:31]
	v_mfma_f32_32x32x16_bf16 v[96:111], v[164:167], v[206:209], v[96:111]
	v_mfma_f32_32x32x16_bf16 v[64:79], v[168:171], v[206:209], v[64:79]
	v_mfma_f32_32x32x16_bf16 v[32:47], v[172:175], v[206:209], v[32:47]
	ds_read_b128 v[176:179], v214 offset:36960
	ds_read_b128 v[160:163], v214 offset:41568
	ds_read_b128 v[180:183], v200 offset:96
	ds_read_b128 v[172:175], v200 offset:4704
	ds_read_b128 v[168:171], v200 offset:9312
	ds_read_b128 v[164:167], v200 offset:13920
	v_mfma_f32_32x32x16_bf16 v[0:15], v[210:213], v[206:209], v[0:15]
	s_cbranch_scc1 .LBB0_207
	s_and_b32 s12, s37, 2
	s_mul_i32 s12, s12, 0x9000
	v_add_u32_e32 v196, s12, v193
	s_cmp_gt_u32 s34, 13
	s_waitcnt vmcnt(7)
	ds_write_b128 v196, v[128:131]
	s_waitcnt vmcnt(6)
	ds_write_b128 v196, v[132:135] offset:36864
	s_waitcnt vmcnt(5)
	ds_write_b128 v196, v[136:139] offset:9216
	s_waitcnt vmcnt(4)
	ds_write_b128 v196, v[140:143] offset:46080
	s_waitcnt vmcnt(3)
	ds_write_b128 v196, v[144:147] offset:18432
	s_waitcnt vmcnt(2)
	ds_write_b128 v196, v[148:151] offset:55296
	s_waitcnt vmcnt(1)
	ds_write_b128 v196, v[152:155] offset:27648
	s_waitcnt vmcnt(0)
	ds_write_b128 v196, v[156:159] offset:64512
	s_cbranch_scc1 .LBB0_206
	s_add_u32 s96, s92, s2
	s_addc_u32 s97, s93, s3
	s_add_u32 s98, s94, s2
	s_addc_u32 s99, s95, s3
	global_load_dwordx4 v[128:131], v248, s[96:97] offset:256
	global_load_dwordx4 v[132:135], v248, s[98:99] offset:256
	global_load_dwordx4 v[136:139], v249, s[96:97] offset:256
	global_load_dwordx4 v[140:143], v249, s[98:99] offset:256
	global_load_dwordx4 v[144:147], v250, s[96:97] offset:256
	global_load_dwordx4 v[148:151], v250, s[98:99] offset:256
	global_load_dwordx4 v[152:155], v251, s[96:97] offset:256
	global_load_dwordx4 v[156:159], v251, s[98:99] offset:256
	s_branch .LBB0_206

.LBB0_212:
	s_and_b64 vcc, exec, s[2:3]
	s_cbranch_vccz .LBB0_203
	v_mov_b32_e32 v185, v234
	v_readlane_b32 s2, v255, 23
	v_ashrrev_i32_e32 v50, 3, v185
	v_add_u32_e32 v0, s4, v50
	v_ashrrev_i32_e32 v1, 31, v0
	v_and_b32_e32 v51, 7, v185
	v_lshlrev_b64 v[0:1], 11, v[0:1]
	v_add_u32_e32 v2, s5, v50
	v_ashrrev_i32_e32 v3, 31, v2
	v_lshlrev_b32_e32 v200, 4, v51
	v_lshl_add_u64 v[0:1], s[20:21], 0, v[0:1]
	v_lshlrev_b64 v[32:33], 11, v[2:3]
	v_readlane_b32 s3, v255, 24
	v_lshl_add_u64 v[34:35], v[0:1], 0, v[200:201]
	v_add_co_u32_e32 v38, vcc, s25, v34
	v_lshl_add_u64 v[2:3], s[2:3], 0, v[32:33]
	v_lshl_add_u64 v[36:37], v[2:3], 0, v[200:201]
	v_addc_co_u32_e32 v39, vcc, 0, v35, vcc
	v_add_co_u32_e32 v40, vcc, s25, v36
	s_mov_b32 s2, 0x60000
	s_nop 0
	v_addc_co_u32_e32 v41, vcc, 0, v37, vcc
	v_add_co_u32_e32 v42, vcc, s47, v34
	global_load_dwordx4 v[0:3], v[34:35], off
	global_load_dwordx4 v[4:7], v[36:37], off
	v_addc_co_u32_e32 v43, vcc, 0, v35, vcc
	v_add_co_u32_e32 v44, vcc, s47, v36
	global_load_dwordx4 v[8:11], v[38:39], off
	global_load_dwordx4 v[12:15], v[40:41], off
	v_addc_co_u32_e32 v45, vcc, 0, v37, vcc
	v_add_co_u32_e32 v46, vcc, s2, v34
	global_load_dwordx4 v[16:19], v[42:43], off
	global_load_dwordx4 v[20:23], v[44:45], off
	v_addc_co_u32_e32 v47, vcc, 0, v35, vcc
	v_add_co_u32_e32 v48, vcc, s2, v36
	v_lshlrev_b32_e32 v184, 3, v51
	s_nop 0
	v_addc_co_u32_e32 v49, vcc, 0, v37, vcc
	global_load_dwordx4 v[24:27], v[46:47], off
	global_load_dwordx4 v[28:31], v[48:49], off
	v_mul_lo_u32 v51, v50, s24
	v_add3_u32 v193, v51, v200, 0
	s_add_i32 s2, s16, s17
	s_add_i32 s2, s2, s0
	v_readfirstlane_b32 s3, v185
	s_ashr_i32 s16, s3, 6
	v_add_u32_e32 v50, s2, v50
	s_ashr_i32 s17, s3, 1
	s_lshl_b32 s2, s16, 7
	v_ashrrev_i32_e32 v51, 31, v50
	v_and_b32_e32 v190, 31, v185
	s_andn2_b32 s17, s17, 63
	s_and_b32 s34, s2, 0x80
	v_lshlrev_b64 v[50:51], 11, v[50:51]
	v_bfe_u32 v191, v185, 5, 1
	v_or_b32_e32 v52, s17, v190
	v_or_b32_e32 v53, s34, v190
	v_or_b32_e32 v32, v32, v200
	v_or_b32_e32 v50, v50, v200
	s_mov_b32 s1, 0x60000
	s_mov_b32 s22, 0
	v_lshlrev_b32_e32 v192, 4, v191
	v_mul_lo_u32 v194, v52, s24
	v_mul_u32_u24_e32 v195, 0x90, v53
	v_lshl_add_u64 v[186:187], s[30:31], 0, v[32:33]
	v_lshl_add_u64 v[188:189], s[10:11], 0, v[50:51]
	s_mov_b64 s[2:3], 0
	s_mov_b32 s35, 2
	s_waitcnt vmcnt(7)
	ds_write_b128 v193, v[0:3]
	s_waitcnt vmcnt(6)
	ds_write_b128 v193, v[4:7] offset:36864
	s_waitcnt vmcnt(5)
	ds_write_b128 v193, v[8:11] offset:9216
	s_waitcnt vmcnt(4)
	ds_write_b128 v193, v[12:15] offset:46080
	s_waitcnt vmcnt(3)
	ds_write_b128 v193, v[16:19] offset:18432
	s_waitcnt vmcnt(2)
	ds_write_b128 v193, v[20:23] offset:55296
	s_waitcnt vmcnt(1)
	ds_write_b128 v193, v[24:27] offset:27648
	s_waitcnt vmcnt(0)
	ds_write_b128 v193, v[28:31] offset:64512
	s_waitcnt lgkmcnt(0)
	s_barrier
	global_load_dwordx4 v[128:131], v[34:35], off offset:128
	global_load_dwordx4 v[132:135], v[36:37], off offset:128
	global_load_dwordx4 v[136:139], v[38:39], off offset:128
	global_load_dwordx4 v[140:143], v[40:41], off offset:128
	global_load_dwordx4 v[144:147], v[42:43], off offset:128
	global_load_dwordx4 v[148:151], v[44:45], off offset:128
	global_load_dwordx4 v[152:155], v[46:47], off offset:128
	global_load_dwordx4 v[156:159], v[48:49], off offset:128
	v_mov_b32_e32 v0, 0
	v_mov_b32_e32 v1, v0
	v_mov_b32_e32 v2, v0
	v_mov_b32_e32 v3, v0
	v_mov_b32_e32 v4, v0
	v_mov_b32_e32 v5, v0
	v_mov_b32_e32 v6, v0
	v_mov_b32_e32 v7, v0
	v_mov_b32_e32 v8, v0
	v_mov_b32_e32 v9, v0
	v_mov_b32_e32 v10, v0
	v_mov_b32_e32 v11, v0
	v_mov_b32_e32 v12, v0
	v_mov_b32_e32 v13, v0
	v_mov_b32_e32 v14, v0
	v_mov_b32_e32 v15, v0
	v_mov_b32_e32 v32, v0
	v_mov_b32_e32 v33, v0
	v_mov_b32_e32 v34, v0
	v_mov_b32_e32 v35, v0
	v_mov_b32_e32 v36, v0
	v_mov_b32_e32 v37, v0
	v_mov_b32_e32 v38, v0
	v_mov_b32_e32 v39, v0
	v_mov_b32_e32 v40, v0
	v_mov_b32_e32 v41, v0
	v_mov_b32_e32 v42, v0
	v_mov_b32_e32 v43, v0
	v_mov_b32_e32 v44, v0
	v_mov_b32_e32 v45, v0
	v_mov_b32_e32 v46, v0
	v_mov_b32_e32 v47, v0
	v_mov_b32_e32 v64, v0
	v_mov_b32_e32 v65, v0
	v_mov_b32_e32 v66, v0
	v_mov_b32_e32 v67, v0
	v_mov_b32_e32 v68, v0
	v_mov_b32_e32 v69, v0
	v_mov_b32_e32 v70, v0
	v_mov_b32_e32 v71, v0
	v_mov_b32_e32 v72, v0
	v_mov_b32_e32 v73, v0
	v_mov_b32_e32 v74, v0
	v_mov_b32_e32 v75, v0
	v_mov_b32_e32 v76, v0
	v_mov_b32_e32 v77, v0
	v_mov_b32_e32 v78, v0
	v_mov_b32_e32 v79, v0
	v_mov_b32_e32 v96, v0
	v_mov_b32_e32 v97, v0
	v_mov_b32_e32 v98, v0
	v_mov_b32_e32 v99, v0
	v_mov_b32_e32 v100, v0
	v_mov_b32_e32 v101, v0
	v_mov_b32_e32 v102, v0
	v_mov_b32_e32 v103, v0
	v_mov_b32_e32 v104, v0
	v_mov_b32_e32 v105, v0
	v_mov_b32_e32 v106, v0
	v_mov_b32_e32 v107, v0
	v_mov_b32_e32 v108, v0
	v_mov_b32_e32 v109, v0
	v_mov_b32_e32 v110, v0
	v_mov_b32_e32 v111, v0
	v_mov_b32_e32 v16, v0
	v_mov_b32_e32 v17, v0
	v_mov_b32_e32 v18, v0
	v_mov_b32_e32 v19, v0
	v_mov_b32_e32 v20, v0
	v_mov_b32_e32 v21, v0
	v_mov_b32_e32 v22, v0
	v_mov_b32_e32 v23, v0
	v_mov_b32_e32 v24, v0
	v_mov_b32_e32 v25, v0
	v_mov_b32_e32 v26, v0
	v_mov_b32_e32 v27, v0
	v_mov_b32_e32 v28, v0
	v_mov_b32_e32 v29, v0
	v_mov_b32_e32 v30, v0
	v_mov_b32_e32 v31, v0
	v_mov_b32_e32 v48, v0
	v_mov_b32_e32 v49, v0
	v_mov_b32_e32 v50, v0
	v_mov_b32_e32 v51, v0
	v_mov_b32_e32 v52, v0
	v_mov_b32_e32 v53, v0
	v_mov_b32_e32 v54, v0
	v_mov_b32_e32 v55, v0
	v_mov_b32_e32 v56, v0
	v_mov_b32_e32 v57, v0
	v_mov_b32_e32 v58, v0
	v_mov_b32_e32 v59, v0
	v_mov_b32_e32 v60, v0
	v_mov_b32_e32 v61, v0
	v_mov_b32_e32 v62, v0
	v_mov_b32_e32 v63, v0
	v_mov_b32_e32 v80, v0
	v_mov_b32_e32 v81, v0
	v_mov_b32_e32 v82, v0
	v_mov_b32_e32 v83, v0
	v_mov_b32_e32 v84, v0
	v_mov_b32_e32 v85, v0
	v_mov_b32_e32 v86, v0
	v_mov_b32_e32 v87, v0
	v_mov_b32_e32 v88, v0
	v_mov_b32_e32 v89, v0
	v_mov_b32_e32 v90, v0
	v_mov_b32_e32 v91, v0
	v_mov_b32_e32 v92, v0
	v_mov_b32_e32 v93, v0
	v_mov_b32_e32 v94, v0
	v_mov_b32_e32 v95, v0
	v_mov_b32_e32 v112, v0
	v_mov_b32_e32 v113, v0
	v_mov_b32_e32 v114, v0
	v_mov_b32_e32 v115, v0
	v_mov_b32_e32 v116, v0
	v_mov_b32_e32 v117, v0
	v_mov_b32_e32 v118, v0
	v_mov_b32_e32 v119, v0
	v_mov_b32_e32 v120, v0
	v_mov_b32_e32 v121, v0
	v_mov_b32_e32 v122, v0
	v_mov_b32_e32 v123, v0
	v_mov_b32_e32 v124, v0
	v_mov_b32_e32 v125, v0
	v_mov_b32_e32 v126, v0
	v_mov_b32_e32 v127, v0
	v_readfirstlane_b32 s92, v188
	v_readfirstlane_b32 s93, v189
	v_readfirstlane_b32 s94, v186
	v_readfirstlane_b32 s95, v187
	s_nop 1
	v_subrev_u32_e32 v248, s92, v188
	v_add_u32_e32 v249, 0x20000, v248
	v_add_u32_e32 v250, 0x40000, v248
	v_add_u32_e32 v251, 0x60000, v248
	s_add_u32 s92, s92, 0x16d00000
	s_addc_u32 s93, s93, 0
	s_add_u32 s94, s94, 0x100000
	s_addc_u32 s95, s95, 0
	s_branch .LBB0_216

.LBB0_216:
	s_add_i32 s12, s35, -2
	s_and_b32 s12, s12, 2
	s_mul_i32 s12, s12, 0x9000
	s_add_i32 s12, s12, 0
	v_add3_u32 v214, s12, v194, v192
	ds_read_b128 v[160:163], v214 offset:36864
	v_add3_u32 v215, s12, v195, v192
	ds_read_b128 v[164:167], v215
	ds_read_b128 v[168:171], v215 offset:4608
	ds_read_b128 v[172:175], v215 offset:9216
	ds_read_b128 v[176:179], v215 offset:13824
	s_cmpk_eq_i32 s2, 0x780
	s_waitcnt lgkmcnt(3)
	v_mfma_f32_32x32x16_bf16 v[112:127], v[160:163], v[164:167], v[112:127]
	s_waitcnt lgkmcnt(2)
	v_mfma_f32_32x32x16_bf16 v[80:95], v[160:163], v[168:171], v[80:95]
	s_waitcnt lgkmcnt(1)
	v_mfma_f32_32x32x16_bf16 v[48:63], v[160:163], v[172:175], v[48:63]
	s_waitcnt lgkmcnt(0)
	v_mfma_f32_32x32x16_bf16 v[16:31], v[160:163], v[176:179], v[16:31]
	ds_read_b128 v[160:163], v214 offset:41472
	s_waitcnt lgkmcnt(0)
	v_mfma_f32_32x32x16_bf16 v[96:111], v[160:163], v[164:167], v[96:111]
	v_mfma_f32_32x32x16_bf16 v[64:79], v[160:163], v[168:171], v[64:79]
	v_mfma_f32_32x32x16_bf16 v[32:47], v[160:163], v[172:175], v[32:47]
	ds_read_b128 v[164:167], v214 offset:36896
	ds_read_b128 v[168:171], v215 offset:32
	ds_read_b128 v[172:175], v215 offset:4640
	ds_read_b128 v[180:183], v215 offset:9248
	ds_read_b128 v[196:199], v215 offset:13856
	ds_read_b128 v[202:205], v214 offset:41504
	v_mfma_f32_32x32x16_bf16 v[0:15], v[160:163], v[176:179], v[0:15]
	s_waitcnt lgkmcnt(4)
	v_mfma_f32_32x32x16_bf16 v[112:127], v[164:167], v[168:171], v[112:127]
	s_waitcnt lgkmcnt(3)
	v_mfma_f32_32x32x16_bf16 v[80:95], v[164:167], v[172:175], v[80:95]
	s_waitcnt lgkmcnt(2)
	v_mfma_f32_32x32x16_bf16 v[48:63], v[164:167], v[180:183], v[48:63]
	s_waitcnt lgkmcnt(1)
	v_mfma_f32_32x32x16_bf16 v[16:31], v[164:167], v[196:199], v[16:31]
	s_waitcnt lgkmcnt(0)
	v_mfma_f32_32x32x16_bf16 v[96:111], v[202:205], v[168:171], v[96:111]
	v_mfma_f32_32x32x16_bf16 v[64:79], v[202:205], v[172:175], v[64:79]
	ds_read_b128 v[160:163], v214 offset:36928
	ds_read_b128 v[206:209], v214 offset:41536
	ds_read_b128 v[164:167], v215 offset:64
	ds_read_b128 v[168:171], v215 offset:4672
	ds_read_b128 v[172:175], v215 offset:9280
	ds_read_b128 v[210:213], v215 offset:13888
	v_mfma_f32_32x32x16_bf16 v[32:47], v[202:205], v[180:183], v[32:47]
	v_mfma_f32_32x32x16_bf16 v[0:15], v[202:205], v[196:199], v[0:15]
	s_waitcnt lgkmcnt(3)
	v_mfma_f32_32x32x16_bf16 v[112:127], v[160:163], v[164:167], v[112:127]
	s_waitcnt lgkmcnt(2)
	v_mfma_f32_32x32x16_bf16 v[80:95], v[160:163], v[168:171], v[80:95]
	s_waitcnt lgkmcnt(1)
	v_mfma_f32_32x32x16_bf16 v[48:63], v[160:163], v[172:175], v[48:63]
	s_waitcnt lgkmcnt(0)
	v_mfma_f32_32x32x16_bf16 v[16:31], v[160:163], v[210:213], v[16:31]
	v_mfma_f32_32x32x16_bf16 v[96:111], v[206:209], v[164:167], v[96:111]
	v_mfma_f32_32x32x16_bf16 v[64:79], v[206:209], v[168:171], v[64:79]
	v_mfma_f32_32x32x16_bf16 v[32:47], v[206:209], v[172:175], v[32:47]
	ds_read_b128 v[176:179], v214 offset:36960
	ds_read_b128 v[160:163], v214 offset:41568
	ds_read_b128 v[180:183], v215 offset:96
	ds_read_b128 v[172:175], v215 offset:4704
	ds_read_b128 v[168:171], v215 offset:9312
	ds_read_b128 v[164:167], v215 offset:13920
	v_mfma_f32_32x32x16_bf16 v[0:15], v[206:209], v[210:213], v[0:15]
	s_cbranch_scc1 .LBB0_215
	s_and_b32 s12, s35, 2
	s_mul_i32 s12, s12, 0x9000
	v_add_u32_e32 v196, s12, v193
	s_cmp_gt_u32 s22, 13
	s_waitcnt vmcnt(7)
	ds_write_b128 v196, v[128:131]
	s_waitcnt vmcnt(6)
	ds_write_b128 v196, v[132:135] offset:36864
	s_waitcnt vmcnt(5)
	ds_write_b128 v196, v[136:139] offset:9216
	s_waitcnt vmcnt(4)
	ds_write_b128 v196, v[140:143] offset:46080
	s_waitcnt vmcnt(3)
	ds_write_b128 v196, v[144:147] offset:18432
	s_waitcnt vmcnt(2)
	ds_write_b128 v196, v[148:151] offset:55296
	s_waitcnt vmcnt(1)
	ds_write_b128 v196, v[152:155] offset:27648
	s_waitcnt vmcnt(0)
	ds_write_b128 v196, v[156:159] offset:64512
	s_cbranch_scc1 .LBB0_214
	s_add_u32 s96, s92, s2
	s_addc_u32 s97, s93, s3
	s_add_u32 s98, s94, s2
	s_addc_u32 s99, s95, s3
	global_load_dwordx4 v[128:131], v248, s[96:97] offset:256
	global_load_dwordx4 v[132:135], v248, s[98:99] offset:256
	global_load_dwordx4 v[136:139], v249, s[96:97] offset:256
	global_load_dwordx4 v[140:143], v249, s[98:99] offset:256
	global_load_dwordx4 v[144:147], v250, s[96:97] offset:256
	global_load_dwordx4 v[148:151], v250, s[98:99] offset:256
	global_load_dwordx4 v[152:155], v251, s[96:97] offset:256
	global_load_dwordx4 v[156:159], v251, s[98:99] offset:256
	s_branch .LBB0_214

.LBB0_444:
	s_and_b32 s2, s43, 7
	s_lshl_b32 s16, s2, 8
	s_and_b32 s2, s44, 7
	v_readlane_b32 s3, v253, 25
	s_or_b32 s2, s2, s3
	s_mul_hi_i32 s3, s44, 0x38e38e39
	s_lshr_b32 s4, s3, 31
	s_lshr_b32 s3, s3, 4
	s_add_i32 s3, s3, s4
	s_lshl_b32 s34, s2, 8
	s_ashr_i32 s2, s44, 3
	s_lshl_b32 s17, s3, 11
	s_mul_hi_i32 s3, s2, 0x38e38e39
	s_lshr_b32 s4, s3, 31
	s_lshr_b32 s3, s3, 1
	s_add_i32 s3, s3, s4
	s_mul_i32 s3, s3, 9
	s_sub_i32 s2, s2, s3
	s_lshl_b32 s35, s2, 8
	s_add_i32 s4, s35, s42
	s_add_i32 s34, s34, s17
	s_and_b32 s2, s4, 0xfffffe00
	s_cmpk_eq_i32 s2, 0x400
	s_cselect_b64 s[2:3], -1, 0
	s_cmpk_gt_i32 s4, 0x87f
	s_cselect_b64 s[4:5], -1, 0
	s_or_b64 s[4:5], s[4:5], s[2:3]
	s_mov_b64 s[2:3], -1
	s_and_b64 vcc, exec, s[4:5]
	s_cbranch_vccz .LBB0_456
	v_mov_b32_e32 v189, v234
	v_readlane_b32 s0, v255, 23
	v_ashrrev_i32_e32 v50, 3, v189
	v_add_u32_e32 v0, s34, v50
	v_ashrrev_i32_e32 v1, 31, v0
	v_lshlrev_b64 v[0:1], 11, v[0:1]
	v_add_u32_e32 v2, s35, v50
	v_lshlrev_b32_e32 v194, 4, v189
	v_ashrrev_i32_e32 v3, 31, v2
	v_and_b32_e32 v200, 0x70, v194
	v_lshl_add_u64 v[0:1], s[20:21], 0, v[0:1]
	v_lshlrev_b64 v[32:33], 11, v[2:3]
	v_readlane_b32 s1, v255, 24
	v_lshl_add_u64 v[34:35], v[0:1], 0, v[200:201]
	v_add_co_u32_e32 v38, vcc, s25, v34
	v_lshl_add_u64 v[2:3], s[0:1], 0, v[32:33]
	v_lshl_add_u64 v[36:37], v[2:3], 0, v[200:201]
	v_addc_co_u32_e32 v39, vcc, 0, v35, vcc
	v_add_co_u32_e32 v40, vcc, s25, v36
	s_mov_b32 s0, 0x60000
	s_nop 0
	v_addc_co_u32_e32 v41, vcc, 0, v37, vcc
	v_add_co_u32_e32 v42, vcc, s47, v34
	global_load_dwordx4 v[0:3], v[34:35], off
	global_load_dwordx4 v[4:7], v[36:37], off
	v_addc_co_u32_e32 v43, vcc, 0, v35, vcc
	v_add_co_u32_e32 v44, vcc, s47, v36
	global_load_dwordx4 v[8:11], v[38:39], off
	global_load_dwordx4 v[12:15], v[40:41], off
	v_addc_co_u32_e32 v45, vcc, 0, v37, vcc
	v_add_co_u32_e32 v46, vcc, s0, v34
	global_load_dwordx4 v[16:19], v[42:43], off
	global_load_dwordx4 v[20:23], v[44:45], off
	v_addc_co_u32_e32 v47, vcc, 0, v35, vcc
	v_add_co_u32_e32 v48, vcc, s0, v36
	v_mul_lo_u32 v51, v50, s24
	s_nop 0
	v_addc_co_u32_e32 v49, vcc, 0, v37, vcc
	global_load_dwordx4 v[24:27], v[46:47], off
	global_load_dwordx4 v[28:31], v[48:49], off
	v_add3_u32 v190, v51, v200, 0
	s_add_i32 s2, s16, s17
	v_readlane_b32 s0, v255, 22
	s_add_i32 s2, s2, s0
	v_readfirstlane_b32 s3, v189
	s_ashr_i32 s5, s3, 6
	v_add_u32_e32 v50, s2, v50
	s_ashr_i32 s22, s3, 1
	s_lshl_b32 s2, s5, 7
	v_ashrrev_i32_e32 v51, 31, v50
	v_and_b32_e32 v195, 31, v189
	s_and_b32 s6, s22, 0xffffffc0
	s_and_b32 s7, s2, 0x80
	v_lshlrev_b64 v[50:51], 11, v[50:51]
	v_bfe_u32 v196, v189, 5, 1
	v_or_b32_e32 v52, s6, v195
	v_or_b32_e32 v53, s7, v195
	v_or_b32_e32 v32, v32, v200
	v_or_b32_e32 v50, v50, v200
	v_mov_b32_e32 v80, 0
	s_mov_b32 s1, 0x60000
	s_mov_b32 s4, 0
	v_lshlrev_b32_e32 v188, 4, v196
	v_mul_lo_u32 v191, v52, s24
	v_mul_u32_u24_e32 v192, 0x90, v53
	v_lshl_add_u64 v[184:185], s[30:31], 0, v[32:33]
	v_lshl_add_u64 v[186:187], s[10:11], 0, v[50:51]
	s_mov_b64 s[2:3], 0
	s_mov_b32 s36, 2
	v_mov_b32_e32 v81, v80
	v_mov_b32_e32 v82, v80
	v_mov_b32_e32 v83, v80
	v_mov_b32_e32 v84, v80
	v_mov_b32_e32 v85, v80
	v_mov_b32_e32 v86, v80
	v_mov_b32_e32 v87, v80
	v_mov_b32_e32 v88, v80
	v_mov_b32_e32 v89, v80
	v_mov_b32_e32 v90, v80
	v_mov_b32_e32 v91, v80
	v_mov_b32_e32 v92, v80
	v_mov_b32_e32 v93, v80
	v_mov_b32_e32 v94, v80
	v_mov_b32_e32 v95, v80
	v_mov_b32_e32 v50, v80
	v_mov_b32_e32 v51, v80
	v_mov_b32_e32 v52, v80
	v_mov_b32_e32 v53, v80
	v_mov_b32_e32 v54, v80
	v_mov_b32_e32 v55, v80
	v_mov_b32_e32 v56, v80
	s_waitcnt vmcnt(7)
	ds_write_b128 v190, v[0:3]
	s_waitcnt vmcnt(6)
	ds_write_b128 v190, v[4:7] offset:36864
	s_waitcnt vmcnt(5)
	ds_write_b128 v190, v[8:11] offset:9216
	s_waitcnt vmcnt(4)
	ds_write_b128 v190, v[12:15] offset:46080
	s_waitcnt vmcnt(3)
	ds_write_b128 v190, v[16:19] offset:18432
	s_waitcnt vmcnt(2)
	ds_write_b128 v190, v[20:23] offset:55296
	s_waitcnt vmcnt(1)
	ds_write_b128 v190, v[24:27] offset:27648
	s_waitcnt vmcnt(0)
	ds_write_b128 v190, v[28:31] offset:64512
	s_waitcnt lgkmcnt(0)
	s_barrier
	global_load_dwordx4 v[128:131], v[34:35], off offset:128
	global_load_dwordx4 v[132:135], v[36:37], off offset:128
	global_load_dwordx4 v[136:139], v[38:39], off offset:128
	global_load_dwordx4 v[140:143], v[40:41], off offset:128
	global_load_dwordx4 v[144:147], v[42:43], off offset:128
	global_load_dwordx4 v[148:151], v[44:45], off offset:128
	global_load_dwordx4 v[152:155], v[46:47], off offset:128
	global_load_dwordx4 v[156:159], v[48:49], off offset:128
	v_mov_b32_e32 v48, v80
	v_mov_b32_e32 v49, v80
	v_mov_b32_e32 v57, v80
	v_mov_b32_e32 v58, v80
	v_mov_b32_e32 v59, v80
	v_mov_b32_e32 v60, v80
	v_mov_b32_e32 v61, v80
	v_mov_b32_e32 v62, v80
	v_mov_b32_e32 v63, v80
	v_mov_b32_e32 v16, v80
	v_mov_b32_e32 v17, v80
	v_mov_b32_e32 v18, v80
	v_mov_b32_e32 v19, v80
	v_mov_b32_e32 v20, v80
	v_mov_b32_e32 v21, v80
	v_mov_b32_e32 v22, v80
	v_mov_b32_e32 v23, v80
	v_mov_b32_e32 v24, v80
	v_mov_b32_e32 v25, v80
	v_mov_b32_e32 v26, v80
	v_mov_b32_e32 v27, v80
	v_mov_b32_e32 v28, v80
	v_mov_b32_e32 v29, v80
	v_mov_b32_e32 v30, v80
	v_mov_b32_e32 v31, v80
	v_mov_b32_e32 v0, v80
	v_mov_b32_e32 v1, v80
	v_mov_b32_e32 v2, v80
	v_mov_b32_e32 v3, v80
	v_mov_b32_e32 v4, v80
	v_mov_b32_e32 v5, v80
	v_mov_b32_e32 v6, v80
	v_mov_b32_e32 v7, v80
	v_mov_b32_e32 v8, v80
	v_mov_b32_e32 v9, v80
	v_mov_b32_e32 v10, v80
	v_mov_b32_e32 v11, v80
	v_mov_b32_e32 v12, v80
	v_mov_b32_e32 v13, v80
	v_mov_b32_e32 v14, v80
	v_mov_b32_e32 v15, v80
	v_mov_b32_e32 v112, v80
	v_mov_b32_e32 v113, v80
	v_mov_b32_e32 v114, v80
	v_mov_b32_e32 v115, v80
	v_mov_b32_e32 v116, v80
	v_mov_b32_e32 v117, v80
	v_mov_b32_e32 v118, v80
	v_mov_b32_e32 v119, v80
	v_mov_b32_e32 v120, v80
	v_mov_b32_e32 v121, v80
	v_mov_b32_e32 v122, v80
	v_mov_b32_e32 v123, v80
	v_mov_b32_e32 v124, v80
	v_mov_b32_e32 v125, v80
	v_mov_b32_e32 v126, v80
	v_mov_b32_e32 v127, v80
	v_mov_b32_e32 v96, v80
	v_mov_b32_e32 v97, v80
	v_mov_b32_e32 v98, v80
	v_mov_b32_e32 v99, v80
	v_mov_b32_e32 v100, v80
	v_mov_b32_e32 v101, v80
	v_mov_b32_e32 v102, v80
	v_mov_b32_e32 v103, v80
	v_mov_b32_e32 v104, v80
	v_mov_b32_e32 v105, v80
	v_mov_b32_e32 v106, v80
	v_mov_b32_e32 v107, v80
	v_mov_b32_e32 v108, v80
	v_mov_b32_e32 v109, v80
	v_mov_b32_e32 v110, v80
	v_mov_b32_e32 v111, v80
	v_mov_b32_e32 v64, v80
	v_mov_b32_e32 v65, v80
	v_mov_b32_e32 v66, v80
	v_mov_b32_e32 v67, v80
	v_mov_b32_e32 v68, v80
	v_mov_b32_e32 v69, v80
	v_mov_b32_e32 v70, v80
	v_mov_b32_e32 v71, v80
	v_mov_b32_e32 v72, v80
	v_mov_b32_e32 v73, v80
	v_mov_b32_e32 v74, v80
	v_mov_b32_e32 v75, v80
	v_mov_b32_e32 v76, v80
	v_mov_b32_e32 v77, v80
	v_mov_b32_e32 v78, v80
	v_mov_b32_e32 v79, v80
	v_mov_b32_e32 v32, v80
	v_mov_b32_e32 v33, v80
	v_mov_b32_e32 v34, v80
	v_mov_b32_e32 v35, v80
	v_mov_b32_e32 v36, v80
	v_mov_b32_e32 v37, v80
	v_mov_b32_e32 v38, v80
	v_mov_b32_e32 v39, v80
	v_mov_b32_e32 v40, v80
	v_mov_b32_e32 v41, v80
	v_mov_b32_e32 v42, v80
	v_mov_b32_e32 v43, v80
	v_mov_b32_e32 v44, v80
	v_mov_b32_e32 v45, v80
	v_mov_b32_e32 v46, v80
	v_mov_b32_e32 v47, v80
	v_readfirstlane_b32 s92, v186
	v_readfirstlane_b32 s93, v187
	v_readfirstlane_b32 s94, v184
	v_readfirstlane_b32 s95, v185
	s_nop 1
	v_subrev_u32_e32 v248, s92, v186
	v_add_u32_e32 v249, 0x20000, v248
	v_add_u32_e32 v250, 0x40000, v248
	v_add_u32_e32 v251, 0x60000, v248
	s_add_u32 s92, s92, 0x16d00000
	s_addc_u32 s93, s93, 0
	s_add_u32 s94, s94, 0x100000
	s_addc_u32 s95, s95, 0
	s_branch .LBB0_448

.LBB0_448:
	s_add_i32 s12, s36, -2
	s_and_b32 s12, s12, 2
	s_mul_i32 s12, s12, 0x9000
	s_add_i32 s12, s12, 0
	v_add3_u32 v193, s12, v192, v188
	ds_read_b128 v[160:163], v193
	ds_read_b128 v[168:171], v193 offset:4608
	ds_read_b128 v[172:175], v193 offset:9216
	ds_read_b128 v[176:179], v193 offset:13824
	v_add3_u32 v197, s12, v191, v188
	ds_read_b128 v[164:167], v197 offset:36864
	s_cmpk_eq_i32 s2, 0x780
	s_waitcnt lgkmcnt(0)
	v_mfma_f32_32x32x16_bf16 v[32:47], v[160:163], v[164:167], v[32:47]
	v_mfma_f32_32x32x16_bf16 v[64:79], v[168:171], v[164:167], v[64:79]
	v_mfma_f32_32x32x16_bf16 v[96:111], v[172:175], v[164:167], v[96:111]
	v_mfma_f32_32x32x16_bf16 v[112:127], v[176:179], v[164:167], v[112:127]
	ds_read_b128 v[164:167], v197 offset:41472
	s_waitcnt lgkmcnt(0)
	v_mfma_f32_32x32x16_bf16 v[0:15], v[160:163], v[164:167], v[0:15]
	v_mfma_f32_32x32x16_bf16 v[16:31], v[168:171], v[164:167], v[16:31]
	v_mfma_f32_32x32x16_bf16 v[48:63], v[172:175], v[164:167], v[48:63]
	ds_read_b128 v[160:163], v197 offset:36896
	ds_read_b128 v[168:171], v193 offset:32
	ds_read_b128 v[172:175], v193 offset:4640
	ds_read_b128 v[180:183], v193 offset:9248
	ds_read_b128 v[202:205], v193 offset:13856
	ds_read_b128 v[206:209], v197 offset:41504
	v_mfma_f32_32x32x16_bf16 v[80:95], v[176:179], v[164:167], v[80:95]
	s_waitcnt lgkmcnt(4)
	v_mfma_f32_32x32x16_bf16 v[32:47], v[168:171], v[160:163], v[32:47]
	s_waitcnt lgkmcnt(3)
	v_mfma_f32_32x32x16_bf16 v[64:79], v[172:175], v[160:163], v[64:79]
	s_waitcnt lgkmcnt(2)
	v_mfma_f32_32x32x16_bf16 v[96:111], v[180:183], v[160:163], v[96:111]
	s_waitcnt lgkmcnt(1)
	v_mfma_f32_32x32x16_bf16 v[112:127], v[202:205], v[160:163], v[112:127]
	s_waitcnt lgkmcnt(0)
	v_mfma_f32_32x32x16_bf16 v[0:15], v[168:171], v[206:209], v[0:15]
	v_mfma_f32_32x32x16_bf16 v[16:31], v[172:175], v[206:209], v[16:31]
	ds_read_b128 v[160:163], v197 offset:36928
	ds_read_b128 v[210:213], v197 offset:41536
	ds_read_b128 v[164:167], v193 offset:64
	ds_read_b128 v[168:171], v193 offset:4672
	ds_read_b128 v[172:175], v193 offset:9280
	ds_read_b128 v[214:217], v193 offset:13888
	v_mfma_f32_32x32x16_bf16 v[48:63], v[180:183], v[206:209], v[48:63]
	v_mfma_f32_32x32x16_bf16 v[80:95], v[202:205], v[206:209], v[80:95]
	s_waitcnt lgkmcnt(3)
	v_mfma_f32_32x32x16_bf16 v[32:47], v[164:167], v[160:163], v[32:47]
	s_waitcnt lgkmcnt(2)
	v_mfma_f32_32x32x16_bf16 v[64:79], v[168:171], v[160:163], v[64:79]
	s_waitcnt lgkmcnt(1)
	v_mfma_f32_32x32x16_bf16 v[96:111], v[172:175], v[160:163], v[96:111]
	s_waitcnt lgkmcnt(0)
	v_mfma_f32_32x32x16_bf16 v[112:127], v[214:217], v[160:163], v[112:127]
	v_mfma_f32_32x32x16_bf16 v[0:15], v[164:167], v[210:213], v[0:15]
	v_mfma_f32_32x32x16_bf16 v[16:31], v[168:171], v[210:213], v[16:31]
	v_mfma_f32_32x32x16_bf16 v[48:63], v[172:175], v[210:213], v[48:63]
	ds_read_b128 v[176:179], v197 offset:36960
	ds_read_b128 v[160:163], v197 offset:41568
	ds_read_b128 v[180:183], v193 offset:96
	ds_read_b128 v[172:175], v193 offset:4704
	ds_read_b128 v[168:171], v193 offset:9312
	ds_read_b128 v[164:167], v193 offset:13920
	v_mfma_f32_32x32x16_bf16 v[80:95], v[214:217], v[210:213], v[80:95]
	s_cbranch_scc1 .LBB0_447
	s_and_b32 s12, s36, 2
	s_mul_i32 s12, s12, 0x9000
	v_add_u32_e32 v193, s12, v190
	s_cmp_gt_u32 s4, 13
	s_waitcnt vmcnt(7)
	ds_write_b128 v193, v[128:131]
	s_waitcnt vmcnt(6)
	ds_write_b128 v193, v[132:135] offset:36864
	s_waitcnt vmcnt(5)
	ds_write_b128 v193, v[136:139] offset:9216
	s_waitcnt vmcnt(4)
	ds_write_b128 v193, v[140:143] offset:46080
	s_waitcnt vmcnt(3)
	ds_write_b128 v193, v[144:147] offset:18432
	s_waitcnt vmcnt(2)
	ds_write_b128 v193, v[148:151] offset:55296
	s_waitcnt vmcnt(1)
	ds_write_b128 v193, v[152:155] offset:27648
	s_waitcnt vmcnt(0)
	ds_write_b128 v193, v[156:159] offset:64512
	s_cbranch_scc1 .LBB0_446
	s_add_u32 s96, s92, s2
	s_addc_u32 s97, s93, s3
	s_add_u32 s98, s94, s2
	s_addc_u32 s99, s95, s3
	global_load_dwordx4 v[128:131], v248, s[96:97] offset:256
	global_load_dwordx4 v[132:135], v248, s[98:99] offset:256
	global_load_dwordx4 v[136:139], v249, s[96:97] offset:256
	global_load_dwordx4 v[140:143], v249, s[98:99] offset:256
	global_load_dwordx4 v[144:147], v250, s[96:97] offset:256
	global_load_dwordx4 v[148:151], v250, s[98:99] offset:256
	global_load_dwordx4 v[152:155], v251, s[96:97] offset:256
	global_load_dwordx4 v[156:159], v251, s[98:99] offset:256
	s_branch .LBB0_446

.LBB0_456:
	s_and_b64 vcc, exec, s[2:3]
	s_cbranch_vccz .LBB0_443
	v_mov_b32_e32 v214, v234
	v_readlane_b32 s0, v255, 23
	v_ashrrev_i32_e32 v40, 3, v214
	v_add_u32_e32 v0, s34, v40
	v_ashrrev_i32_e32 v1, 31, v0
	s_waitcnt vmcnt(17)
	v_and_b32_e32 v160, 7, v214
	v_lshlrev_b64 v[0:1], 11, v[0:1]
	v_add_u32_e32 v2, s35, v40
	v_ashrrev_i32_e32 v3, 31, v2
	v_lshlrev_b32_e32 v184, 4, v160
	v_lshl_add_u64 v[0:1], s[20:21], 0, v[0:1]
	v_mov_b32_e32 v185, v201
	v_lshlrev_b64 v[38:39], 11, v[2:3]
	v_readlane_b32 s1, v255, 24
	v_lshl_add_u64 v[48:49], v[0:1], 0, v[184:185]
	v_add_co_u32_e32 v52, vcc, s25, v48
	v_lshl_add_u64 v[2:3], s[0:1], 0, v[38:39]
	v_lshl_add_u64 v[50:51], v[2:3], 0, v[184:185]
	v_addc_co_u32_e32 v53, vcc, 0, v49, vcc
	v_add_co_u32_e32 v54, vcc, s25, v50
	s_mov_b32 s0, 0x60000
	s_nop 0
	v_addc_co_u32_e32 v55, vcc, 0, v51, vcc
	v_add_co_u32_e32 v56, vcc, s47, v48
	global_load_dwordx4 v[6:9], v[48:49], off
	global_load_dwordx4 v[10:13], v[50:51], off
	v_addc_co_u32_e32 v57, vcc, 0, v49, vcc
	v_add_co_u32_e32 v58, vcc, s47, v50
	global_load_dwordx4 v[14:17], v[52:53], off
	global_load_dwordx4 v[18:21], v[54:55], off
	v_addc_co_u32_e32 v59, vcc, 0, v51, vcc
	v_add_co_u32_e32 v60, vcc, s0, v48
	global_load_dwordx4 v[22:25], v[56:57], off
	global_load_dwordx4 v[26:29], v[58:59], off
	v_addc_co_u32_e32 v61, vcc, 0, v49, vcc
	v_add_co_u32_e32 v62, vcc, s0, v50
	v_mul_lo_u32 v41, v40, s24
	s_nop 0
	v_addc_co_u32_e32 v63, vcc, 0, v51, vcc
	global_load_dwordx4 v[30:33], v[60:61], off
	global_load_dwordx4 v[34:37], v[62:63], off
	v_add3_u32 v185, v41, v184, 0
	s_add_i32 s6, s16, s17
	v_readlane_b32 s0, v255, 22
	s_add_i32 s7, s6, s0
	v_readfirstlane_b32 s12, v214
	s_ashr_i32 s6, s12, 6
	v_add_u32_e32 v40, s7, v40
	s_ashr_i32 s12, s12, 1
	s_lshl_b32 s13, s6, 7
	v_ashrrev_i32_e32 v41, 31, v40
	v_and_b32_e32 v209, 31, v214
	s_and_b32 s7, s12, 0xffffffc0
	s_and_b32 s16, s13, 0x80
	v_lshlrev_b64 v[40:41], 11, v[40:41]
	v_mov_b32_e32 v0, 0
	v_or_b32_e32 v42, s7, v209
	v_or_b32_e32 v43, s16, v209
	v_or_b32_e32 v38, v38, v184
	v_or_b32_e32 v40, v40, v184
	v_bfe_u32 v187, v214, 5, 1
	s_mov_b32 s1, 0x60000
	s_mov_b32 s4, 0
	s_mov_b64 s[2:3], 0
	s_mov_b32 s5, 2
	v_mov_b32_e32 v1, v0
	v_mov_b32_e32 v2, v0
	v_mov_b32_e32 v3, v0
	v_mov_b32_e32 v4, v0
	v_mov_b32_e32 v5, v0
	v_mul_lo_u32 v192, v42, s24
	v_mul_u32_u24_e32 v193, 0x90, v43
	v_lshl_add_u64 v[188:189], s[30:31], 0, v[38:39]
	v_lshl_add_u64 v[190:191], s[10:11], 0, v[40:41]
	v_mov_b32_e32 v38, v0
	v_mov_b32_e32 v39, v0
	v_mov_b32_e32 v40, v0
	v_mov_b32_e32 v41, v0
	v_mov_b32_e32 v42, v0
	v_mov_b32_e32 v43, v0
	v_mov_b32_e32 v44, v0
	v_mov_b32_e32 v45, v0
	v_mov_b32_e32 v46, v0
	v_mov_b32_e32 v47, v0
	v_mov_b32_e32 v64, v0
	v_mov_b32_e32 v65, v0
	v_mov_b32_e32 v66, v0
	v_mov_b32_e32 v67, v0
	v_mov_b32_e32 v68, v0
	v_mov_b32_e32 v69, v0
	v_mov_b32_e32 v70, v0
	s_waitcnt vmcnt(7)
	ds_write_b128 v185, v[6:9]
	s_waitcnt vmcnt(6)
	ds_write_b128 v185, v[10:13] offset:36864
	s_waitcnt vmcnt(5)
	ds_write_b128 v185, v[14:17] offset:9216
	s_waitcnt vmcnt(4)
	ds_write_b128 v185, v[18:21] offset:46080
	s_waitcnt vmcnt(3)
	ds_write_b128 v185, v[22:25] offset:18432
	s_waitcnt vmcnt(2)
	ds_write_b128 v185, v[26:29] offset:55296
	s_waitcnt vmcnt(1)
	ds_write_b128 v185, v[30:33] offset:27648
	s_waitcnt vmcnt(0)
	ds_write_b128 v185, v[34:37] offset:64512
	s_waitcnt lgkmcnt(0)
	s_barrier
	global_load_dwordx4 v[128:131], v[48:49], off offset:128
	global_load_dwordx4 v[132:135], v[50:51], off offset:128
	global_load_dwordx4 v[136:139], v[52:53], off offset:128
	global_load_dwordx4 v[140:143], v[54:55], off offset:128
	global_load_dwordx4 v[144:147], v[56:57], off offset:128
	global_load_dwordx4 v[148:151], v[58:59], off offset:128
	global_load_dwordx4 v[152:155], v[60:61], off offset:128
	global_load_dwordx4 v[156:159], v[62:63], off offset:128
	v_mov_b32_e32 v6, v0
	v_mov_b32_e32 v7, v0
	v_mov_b32_e32 v8, v0
	v_mov_b32_e32 v9, v0
	v_mov_b32_e32 v10, v0
	v_mov_b32_e32 v11, v0
	v_mov_b32_e32 v12, v0
	v_mov_b32_e32 v13, v0
	v_mov_b32_e32 v14, v0
	v_mov_b32_e32 v15, v0
	v_mov_b32_e32 v16, v0
	v_mov_b32_e32 v17, v0
	v_mov_b32_e32 v18, v0
	v_mov_b32_e32 v19, v0
	v_mov_b32_e32 v20, v0
	v_mov_b32_e32 v21, v0
	v_mov_b32_e32 v22, v0
	v_mov_b32_e32 v23, v0
	v_mov_b32_e32 v24, v0
	v_mov_b32_e32 v25, v0
	v_mov_b32_e32 v26, v0
	v_mov_b32_e32 v27, v0
	v_mov_b32_e32 v28, v0
	v_mov_b32_e32 v29, v0
	v_mov_b32_e32 v30, v0
	v_mov_b32_e32 v31, v0
	v_mov_b32_e32 v32, v0
	v_mov_b32_e32 v33, v0
	v_mov_b32_e32 v34, v0
	v_mov_b32_e32 v35, v0
	v_mov_b32_e32 v36, v0
	v_mov_b32_e32 v37, v0
	v_mov_b32_e32 v71, v0
	v_mov_b32_e32 v72, v0
	v_mov_b32_e32 v73, v0
	v_mov_b32_e32 v74, v0
	v_mov_b32_e32 v75, v0
	v_mov_b32_e32 v76, v0
	v_mov_b32_e32 v77, v0
	v_mov_b32_e32 v78, v0
	v_mov_b32_e32 v79, v0
	v_mov_b32_e32 v48, v0
	v_mov_b32_e32 v49, v0
	v_mov_b32_e32 v50, v0
	v_mov_b32_e32 v51, v0
	v_mov_b32_e32 v52, v0
	v_mov_b32_e32 v53, v0
	v_mov_b32_e32 v54, v0
	v_mov_b32_e32 v55, v0
	v_mov_b32_e32 v56, v0
	v_mov_b32_e32 v57, v0
	v_mov_b32_e32 v58, v0
	v_mov_b32_e32 v59, v0
	v_mov_b32_e32 v60, v0
	v_mov_b32_e32 v61, v0
	v_mov_b32_e32 v62, v0
	v_mov_b32_e32 v63, v0
	v_mov_b32_e32 v80, v0
	v_mov_b32_e32 v81, v0
	v_mov_b32_e32 v82, v0
	v_mov_b32_e32 v83, v0
	v_mov_b32_e32 v84, v0
	v_mov_b32_e32 v85, v0
	v_mov_b32_e32 v86, v0
	v_mov_b32_e32 v87, v0
	v_mov_b32_e32 v88, v0
	v_mov_b32_e32 v89, v0
	v_mov_b32_e32 v90, v0
	v_mov_b32_e32 v91, v0
	v_mov_b32_e32 v92, v0
	v_mov_b32_e32 v93, v0
	v_mov_b32_e32 v94, v0
	v_mov_b32_e32 v95, v0
	v_mov_b32_e32 v96, v0
	v_mov_b32_e32 v97, v0
	v_mov_b32_e32 v98, v0
	v_mov_b32_e32 v99, v0
	v_mov_b32_e32 v100, v0
	v_mov_b32_e32 v101, v0
	v_mov_b32_e32 v102, v0
	v_mov_b32_e32 v103, v0
	v_mov_b32_e32 v104, v0
	v_mov_b32_e32 v105, v0
	v_mov_b32_e32 v106, v0
	v_mov_b32_e32 v107, v0
	v_mov_b32_e32 v108, v0
	v_mov_b32_e32 v109, v0
	v_mov_b32_e32 v110, v0
	v_mov_b32_e32 v111, v0
	v_mov_b32_e32 v112, v0
	v_mov_b32_e32 v113, v0
	v_mov_b32_e32 v114, v0
	v_mov_b32_e32 v115, v0
	v_mov_b32_e32 v116, v0
	v_mov_b32_e32 v117, v0
	v_mov_b32_e32 v118, v0
	v_mov_b32_e32 v119, v0
	v_mov_b32_e32 v120, v0
	v_mov_b32_e32 v121, v0
	v_mov_b32_e32 v122, v0
	v_mov_b32_e32 v123, v0
	v_mov_b32_e32 v124, v0
	v_mov_b32_e32 v125, v0
	v_mov_b32_e32 v126, v0
	v_mov_b32_e32 v127, v0
	v_lshlrev_b32_e32 v186, 3, v160
	v_lshlrev_b32_e32 v194, 4, v187
	v_readfirstlane_b32 s92, v190
	v_readfirstlane_b32 s93, v191
	v_readfirstlane_b32 s94, v188
	v_readfirstlane_b32 s95, v189
	s_nop 1
	v_subrev_u32_e32 v248, s92, v190
	v_add_u32_e32 v249, 0x20000, v248
	v_add_u32_e32 v250, 0x40000, v248
	v_add_u32_e32 v251, 0x60000, v248
	s_add_u32 s92, s92, 0x16d00000
	s_addc_u32 s93, s93, 0
	s_add_u32 s94, s94, 0x100000
	s_addc_u32 s95, s95, 0
	s_branch .LBB0_460

.LBB0_460:
	s_add_i32 s12, s5, -2
	s_and_b32 s12, s12, 2
	s_mul_i32 s12, s12, 0x9000
	s_add_i32 s12, s12, 0
	v_add3_u32 v195, s12, v192, v194
	ds_read_b128 v[160:163], v195 offset:36864
	v_add3_u32 v200, s12, v193, v194
	ds_read_b128 v[164:167], v200
	ds_read_b128 v[168:171], v200 offset:4608
	ds_read_b128 v[172:175], v200 offset:9216
	ds_read_b128 v[176:179], v200 offset:13824
	s_cmpk_eq_i32 s2, 0x780
	s_waitcnt lgkmcnt(3)
	v_mfma_f32_32x32x16_bf16 v[112:127], v[160:163], v[164:167], v[112:127]
	s_waitcnt lgkmcnt(2)
	v_mfma_f32_32x32x16_bf16 v[96:111], v[160:163], v[168:171], v[96:111]
	s_waitcnt lgkmcnt(1)
	v_mfma_f32_32x32x16_bf16 v[80:95], v[160:163], v[172:175], v[80:95]
	s_waitcnt lgkmcnt(0)
	v_mfma_f32_32x32x16_bf16 v[48:63], v[160:163], v[176:179], v[48:63]
	ds_read_b128 v[160:163], v195 offset:41472
	s_waitcnt lgkmcnt(0)
	v_mfma_f32_32x32x16_bf16 v[64:79], v[160:163], v[164:167], v[64:79]
	v_mfma_f32_32x32x16_bf16 v[32:47], v[160:163], v[168:171], v[32:47]
	v_mfma_f32_32x32x16_bf16 v[16:31], v[160:163], v[172:175], v[16:31]
	ds_read_b128 v[164:167], v195 offset:36896
	ds_read_b128 v[168:171], v200 offset:32
	ds_read_b128 v[172:175], v200 offset:4640
	ds_read_b128 v[180:183], v200 offset:9248
	ds_read_b128 v[196:199], v200 offset:13856
	ds_read_b128 v[202:205], v195 offset:41504
	v_mfma_f32_32x32x16_bf16 v[0:15], v[160:163], v[176:179], v[0:15]
	s_waitcnt lgkmcnt(4)
	v_mfma_f32_32x32x16_bf16 v[112:127], v[164:167], v[168:171], v[112:127]
	s_waitcnt lgkmcnt(3)
	v_mfma_f32_32x32x16_bf16 v[96:111], v[164:167], v[172:175], v[96:111]
	s_waitcnt lgkmcnt(2)
	v_mfma_f32_32x32x16_bf16 v[80:95], v[164:167], v[180:183], v[80:95]
	s_waitcnt lgkmcnt(1)
	v_mfma_f32_32x32x16_bf16 v[48:63], v[164:167], v[196:199], v[48:63]
	s_waitcnt lgkmcnt(0)
	v_mfma_f32_32x32x16_bf16 v[64:79], v[202:205], v[168:171], v[64:79]
	v_mfma_f32_32x32x16_bf16 v[32:47], v[202:205], v[172:175], v[32:47]
	ds_read_b128 v[160:163], v195 offset:36928
	ds_read_b128 v[210:213], v195 offset:41536
	ds_read_b128 v[164:167], v200 offset:64
	ds_read_b128 v[168:171], v200 offset:4672
	ds_read_b128 v[172:175], v200 offset:9280
	ds_read_b128 v[216:219], v200 offset:13888
	v_mfma_f32_32x32x16_bf16 v[16:31], v[202:205], v[180:183], v[16:31]
	v_mfma_f32_32x32x16_bf16 v[0:15], v[202:205], v[196:199], v[0:15]
	s_waitcnt lgkmcnt(3)
	v_mfma_f32_32x32x16_bf16 v[112:127], v[160:163], v[164:167], v[112:127]
	s_waitcnt lgkmcnt(2)
	v_mfma_f32_32x32x16_bf16 v[96:111], v[160:163], v[168:171], v[96:111]
	s_waitcnt lgkmcnt(1)
	v_mfma_f32_32x32x16_bf16 v[80:95], v[160:163], v[172:175], v[80:95]
	s_waitcnt lgkmcnt(0)
	v_mfma_f32_32x32x16_bf16 v[48:63], v[160:163], v[216:219], v[48:63]
	v_mfma_f32_32x32x16_bf16 v[64:79], v[210:213], v[164:167], v[64:79]
	v_mfma_f32_32x32x16_bf16 v[32:47], v[210:213], v[168:171], v[32:47]
	v_mfma_f32_32x32x16_bf16 v[16:31], v[210:213], v[172:175], v[16:31]
	ds_read_b128 v[176:179], v195 offset:36960
	ds_read_b128 v[160:163], v195 offset:41568
	ds_read_b128 v[180:183], v200 offset:96
	ds_read_b128 v[172:175], v200 offset:4704
	ds_read_b128 v[168:171], v200 offset:9312
	ds_read_b128 v[164:167], v200 offset:13920
	v_mfma_f32_32x32x16_bf16 v[0:15], v[210:213], v[216:219], v[0:15]
	s_cbranch_scc1 .LBB0_459
	s_and_b32 s12, s5, 2
	s_mul_i32 s12, s12, 0x9000
	v_add_u32_e32 v195, s12, v185
	s_cmp_gt_u32 s4, 13
	s_waitcnt vmcnt(7)
	ds_write_b128 v195, v[128:131]
	s_waitcnt vmcnt(6)
	ds_write_b128 v195, v[132:135] offset:36864
	s_waitcnt vmcnt(5)
	ds_write_b128 v195, v[136:139] offset:9216
	s_waitcnt vmcnt(4)
	ds_write_b128 v195, v[140:143] offset:46080
	s_waitcnt vmcnt(3)
	ds_write_b128 v195, v[144:147] offset:18432
	s_waitcnt vmcnt(2)
	ds_write_b128 v195, v[148:151] offset:55296
	s_waitcnt vmcnt(1)
	ds_write_b128 v195, v[152:155] offset:27648
	s_waitcnt vmcnt(0)
	ds_write_b128 v195, v[156:159] offset:64512
	s_cbranch_scc1 .LBB0_458
	s_add_u32 s96, s92, s2
	s_addc_u32 s97, s93, s3
	s_add_u32 s98, s94, s2
	s_addc_u32 s99, s95, s3
	global_load_dwordx4 v[128:131], v248, s[96:97] offset:256
	global_load_dwordx4 v[132:135], v248, s[98:99] offset:256
	global_load_dwordx4 v[136:139], v249, s[96:97] offset:256
	global_load_dwordx4 v[140:143], v249, s[98:99] offset:256
	global_load_dwordx4 v[144:147], v250, s[96:97] offset:256
	global_load_dwordx4 v[148:151], v250, s[98:99] offset:256
	global_load_dwordx4 v[152:155], v251, s[96:97] offset:256
	global_load_dwordx4 v[156:159], v251, s[98:99] offset:256
	s_branch .LBB0_458

.LBB0_637:
	s_and_b32 s2, s17, 7
	v_readlane_b32 s3, v253, 25
	s_or_b32 s2, s2, s3
	s_ashr_i32 s3, s17, 31
	s_lshr_b32 s3, s3, 27
	s_add_i32 s3, s17, s3
	s_lshl_b32 s22, s2, 8
	s_ashr_i32 s2, s17, 3
	s_lshl_b32 s3, s3, 6
	s_lshr_b32 s12, s2, 30
	s_and_b32 s3, s3, 0xfffff800
	s_add_i32 s12, s2, s12
	v_mov_b32_e32 v187, v234
	s_add_i32 s22, s22, s3
	s_and_b32 s12, s12, 0xfffffc
	s_sub_i32 s2, s2, s12
	v_ashrrev_i32_e32 v50, 3, v187
	v_add_u32_e32 v0, s22, v50
	s_lshl_b32 s36, s2, 8
	v_ashrrev_i32_e32 v1, 31, v0
	v_and_b32_e32 v51, 7, v187
	v_add_u32_e32 v2, s36, v50
	v_lshlrev_b64 v[0:1], 11, v[0:1]
	v_ashrrev_i32_e32 v3, 31, v2
	v_lshlrev_b32_e32 v184, 4, v51
	v_lshl_add_u64 v[0:1], s[20:21], 0, v[0:1]
	v_mov_b32_e32 v185, v201
	v_lshlrev_b64 v[32:33], 11, v[2:3]
	v_lshl_add_u64 v[34:35], v[0:1], 0, v[184:185]
	v_lshl_add_u64 v[2:3], s[6:7], 0, v[32:33]
	v_add_co_u32_e32 v38, vcc, s25, v34
	v_lshl_add_u64 v[36:37], v[2:3], 0, v[184:185]
	s_nop 0
	v_addc_co_u32_e32 v39, vcc, 0, v35, vcc
	v_add_co_u32_e32 v40, vcc, s25, v36
	s_mov_b32 s0, 0x60000
	s_nop 0
	v_addc_co_u32_e32 v41, vcc, 0, v37, vcc
	v_add_co_u32_e32 v42, vcc, s47, v34
	global_load_dwordx4 v[0:3], v[34:35], off
	global_load_dwordx4 v[4:7], v[36:37], off
	v_addc_co_u32_e32 v43, vcc, 0, v35, vcc
	v_add_co_u32_e32 v44, vcc, s47, v36
	global_load_dwordx4 v[8:11], v[38:39], off
	global_load_dwordx4 v[12:15], v[40:41], off
	v_addc_co_u32_e32 v45, vcc, 0, v37, vcc
	v_add_co_u32_e32 v46, vcc, s0, v34
	global_load_dwordx4 v[16:19], v[42:43], off
	global_load_dwordx4 v[20:23], v[44:45], off
	v_addc_co_u32_e32 v47, vcc, 0, v35, vcc
	v_add_co_u32_e32 v48, vcc, s0, v36
	v_lshlrev_b32_e32 v186, 3, v51
	s_nop 0
	v_addc_co_u32_e32 v49, vcc, 0, v37, vcc
	global_load_dwordx4 v[24:27], v[46:47], off
	global_load_dwordx4 v[28:31], v[48:49], off
	v_mul_lo_u32 v51, v50, s24
	v_add3_u32 v193, v51, v184, 0
	v_readfirstlane_b32 s12, v187
	s_ashr_i32 s37, s12, 6
	s_and_b32 s2, s16, 7
	s_lshl_b32 s13, s37, 7
	s_lshl_b32 s2, s2, 8
	v_and_b32_e32 v185, 31, v187
	s_and_b32 s39, s13, 0x80
	s_ashr_i32 s40, s12, 1
	s_andn2_b32 s40, s40, 63
	s_or_b32 s2, s2, s3
	s_add_i32 s2, s2, s15
	v_bfe_u32 v192, v187, 5, 1
	v_or_b32_e32 v32, v32, v184
	s_mov_b32 s38, 0
	v_lshlrev_b32_e32 v195, 4, v192
	v_lshl_add_u64 v[188:189], s[30:31], 0, v[32:33]
	s_mov_b32 s41, 0
	s_waitcnt vmcnt(7)
	ds_write_b128 v193, v[0:3]
	s_waitcnt vmcnt(6)
	ds_write_b128 v193, v[4:7] offset:36864
	s_waitcnt vmcnt(5)
	ds_write_b128 v193, v[8:11] offset:9216
	s_waitcnt vmcnt(4)
	ds_write_b128 v193, v[12:15] offset:46080
	s_waitcnt vmcnt(3)
	ds_write_b128 v193, v[16:19] offset:18432
	s_waitcnt vmcnt(2)
	ds_write_b128 v193, v[20:23] offset:55296
	s_waitcnt vmcnt(1)
	ds_write_b128 v193, v[24:27] offset:27648
	s_waitcnt vmcnt(0)
	ds_write_b128 v193, v[28:31] offset:64512
	s_waitcnt lgkmcnt(0)
	s_barrier
	global_load_dwordx4 v[156:159], v[48:49], off offset:128
	global_load_dwordx4 v[152:155], v[46:47], off offset:128
	global_load_dwordx4 v[148:151], v[44:45], off offset:128
	global_load_dwordx4 v[144:147], v[42:43], off offset:128
	global_load_dwordx4 v[140:143], v[40:41], off offset:128
	global_load_dwordx4 v[136:139], v[38:39], off offset:128
	global_load_dwordx4 v[132:135], v[36:37], off offset:128
	global_load_dwordx4 v[128:131], v[34:35], off offset:128
	v_or_b32_e32 v0, s39, v185
	v_mul_u32_u24_e32 v194, 0x90, v0
	v_or_b32_e32 v0, s40, v185
	v_mul_lo_u32 v196, v0, s24
	v_add_u32_e32 v0, s2, v50
	v_ashrrev_i32_e32 v1, 31, v0
	v_lshlrev_b64 v[0:1], 11, v[0:1]
	v_or_b32_e32 v0, v0, v184
	v_lshl_add_u64 v[190:191], s[10:11], 0, v[0:1]
	v_mov_b32_e32 v0, 0
	s_mov_b64 s[2:3], 0
	v_mov_b32_e32 v1, v0
	v_mov_b32_e32 v2, v0
	v_mov_b32_e32 v3, v0
	v_mov_b32_e32 v4, v0
	v_mov_b32_e32 v5, v0
	v_mov_b32_e32 v6, v0
	v_mov_b32_e32 v7, v0
	v_mov_b32_e32 v8, v0
	v_mov_b32_e32 v9, v0
	v_mov_b32_e32 v10, v0
	v_mov_b32_e32 v11, v0
	v_mov_b32_e32 v12, v0
	v_mov_b32_e32 v13, v0
	v_mov_b32_e32 v14, v0
	v_mov_b32_e32 v15, v0
	v_mov_b32_e32 v32, v0
	v_mov_b32_e32 v33, v0
	v_mov_b32_e32 v34, v0
	v_mov_b32_e32 v35, v0
	v_mov_b32_e32 v36, v0
	v_mov_b32_e32 v37, v0
	v_mov_b32_e32 v38, v0
	v_mov_b32_e32 v39, v0
	v_mov_b32_e32 v40, v0
	v_mov_b32_e32 v41, v0
	v_mov_b32_e32 v42, v0
	v_mov_b32_e32 v43, v0
	v_mov_b32_e32 v44, v0
	v_mov_b32_e32 v45, v0
	v_mov_b32_e32 v46, v0
	v_mov_b32_e32 v47, v0
	v_mov_b32_e32 v64, v0
	v_mov_b32_e32 v65, v0
	v_mov_b32_e32 v66, v0
	v_mov_b32_e32 v67, v0
	v_mov_b32_e32 v68, v0
	v_mov_b32_e32 v69, v0
	v_mov_b32_e32 v70, v0
	v_mov_b32_e32 v71, v0
	v_mov_b32_e32 v72, v0
	v_mov_b32_e32 v73, v0
	v_mov_b32_e32 v74, v0
	v_mov_b32_e32 v75, v0
	v_mov_b32_e32 v76, v0
	v_mov_b32_e32 v77, v0
	v_mov_b32_e32 v78, v0
	v_mov_b32_e32 v79, v0
	v_mov_b32_e32 v96, v0
	v_mov_b32_e32 v97, v0
	v_mov_b32_e32 v98, v0
	v_mov_b32_e32 v99, v0
	v_mov_b32_e32 v100, v0
	v_mov_b32_e32 v101, v0
	v_mov_b32_e32 v102, v0
	v_mov_b32_e32 v103, v0
	v_mov_b32_e32 v104, v0
	v_mov_b32_e32 v105, v0
	v_mov_b32_e32 v106, v0
	v_mov_b32_e32 v107, v0
	v_mov_b32_e32 v108, v0
	v_mov_b32_e32 v109, v0
	v_mov_b32_e32 v110, v0
	v_mov_b32_e32 v111, v0
	v_mov_b32_e32 v16, v0
	v_mov_b32_e32 v17, v0
	v_mov_b32_e32 v18, v0
	v_mov_b32_e32 v19, v0
	v_mov_b32_e32 v20, v0
	v_mov_b32_e32 v21, v0
	v_mov_b32_e32 v22, v0
	v_mov_b32_e32 v23, v0
	v_mov_b32_e32 v24, v0
	v_mov_b32_e32 v25, v0
	v_mov_b32_e32 v26, v0
	v_mov_b32_e32 v27, v0
	v_mov_b32_e32 v28, v0
	v_mov_b32_e32 v29, v0
	v_mov_b32_e32 v30, v0
	v_mov_b32_e32 v31, v0
	v_mov_b32_e32 v48, v0
	v_mov_b32_e32 v49, v0
	v_mov_b32_e32 v50, v0
	v_mov_b32_e32 v51, v0
	v_mov_b32_e32 v52, v0
	v_mov_b32_e32 v53, v0
	v_mov_b32_e32 v54, v0
	v_mov_b32_e32 v55, v0
	v_mov_b32_e32 v56, v0
	v_mov_b32_e32 v57, v0
	v_mov_b32_e32 v58, v0
	v_mov_b32_e32 v59, v0
	v_mov_b32_e32 v60, v0
	v_mov_b32_e32 v61, v0
	v_mov_b32_e32 v62, v0
	v_mov_b32_e32 v63, v0
	v_mov_b32_e32 v80, v0
	v_mov_b32_e32 v81, v0
	v_mov_b32_e32 v82, v0
	v_mov_b32_e32 v83, v0
	v_mov_b32_e32 v84, v0
	v_mov_b32_e32 v85, v0
	v_mov_b32_e32 v86, v0
	v_mov_b32_e32 v87, v0
	v_mov_b32_e32 v88, v0
	v_mov_b32_e32 v89, v0
	v_mov_b32_e32 v90, v0
	v_mov_b32_e32 v91, v0
	v_mov_b32_e32 v92, v0
	v_mov_b32_e32 v93, v0
	v_mov_b32_e32 v94, v0
	v_mov_b32_e32 v95, v0
	v_mov_b32_e32 v112, v0
	v_mov_b32_e32 v113, v0
	v_mov_b32_e32 v114, v0
	v_mov_b32_e32 v115, v0
	v_mov_b32_e32 v116, v0
	v_mov_b32_e32 v117, v0
	v_mov_b32_e32 v118, v0
	v_mov_b32_e32 v119, v0
	v_mov_b32_e32 v120, v0
	v_mov_b32_e32 v121, v0
	v_mov_b32_e32 v122, v0
	v_mov_b32_e32 v123, v0
	v_mov_b32_e32 v124, v0
	v_mov_b32_e32 v125, v0
	v_mov_b32_e32 v126, v0
	v_mov_b32_e32 v127, v0
	v_readfirstlane_b32 s92, v190
	v_readfirstlane_b32 s93, v191
	v_readfirstlane_b32 s94, v188
	v_readfirstlane_b32 s95, v189
	s_nop 1
	v_subrev_u32_e32 v248, s92, v190
	v_add_u32_e32 v249, 0x20000, v248
	v_add_u32_e32 v250, 0x40000, v248
	v_add_u32_e32 v251, 0x60000, v248
	s_add_u32 s92, s92, 0x16d00000
	s_addc_u32 s93, s93, 0
	s_add_u32 s94, s94, 0x700000
	s_addc_u32 s95, s95, 0
	s_branch .LBB0_640

.LBB0_642:
	s_andn2_b64 vcc, exec, s[34:35]
	s_cbranch_vccnz .LBB0_645
	s_add_i32 s38, s38, 2
	s_and_b32 s12, s38, 2
	s_mul_i32 s12, s12, 0x9000
	v_add_u32_e32 v197, s12, v193
	s_cmpk_eq_i32 s2, 0x700
	s_waitcnt vmcnt(0)
	ds_write_b128 v197, v[128:131]
	ds_write_b128 v197, v[132:135] offset:36864
	ds_write_b128 v197, v[136:139] offset:9216
	ds_write_b128 v197, v[140:143] offset:46080
	ds_write_b128 v197, v[144:147] offset:18432
	ds_write_b128 v197, v[148:151] offset:55296
	ds_write_b128 v197, v[152:155] offset:27648
	ds_write_b128 v197, v[156:159] offset:64512
	s_cbranch_scc1 .LBB0_638
	s_add_u32 s96, s92, s2
	s_addc_u32 s97, s93, s3
	s_add_u32 s98, s94, s2
	s_addc_u32 s99, s95, s3
	global_load_dwordx4 v[128:131], v248, s[96:97] offset:256
	global_load_dwordx4 v[132:135], v248, s[98:99] offset:256
	global_load_dwordx4 v[136:139], v249, s[96:97] offset:256
	global_load_dwordx4 v[140:143], v249, s[98:99] offset:256
	global_load_dwordx4 v[144:147], v250, s[96:97] offset:256
	global_load_dwordx4 v[148:151], v250, s[98:99] offset:256
	global_load_dwordx4 v[152:155], v251, s[96:97] offset:256
	global_load_dwordx4 v[156:159], v251, s[98:99] offset:256
	s_branch .LBB0_638

.LBB0_755:
	s_and_b32 s4, s52, 7
	v_readlane_b32 s5, v253, 25
	s_or_b32 s4, s4, s5
	s_mul_hi_i32 s5, s52, 0x2e8ba2e9
	s_lshr_b32 s6, s5, 31
	s_lshr_b32 s5, s5, 5
	s_add_i32 s5, s5, s6
	s_lshl_b32 s22, s4, 8
	s_ashr_i32 s4, s52, 3
	s_lshl_b32 s12, s5, 11
	s_mul_hi_i32 s5, s4, 0x2e8ba2e9
	s_lshr_b32 s6, s5, 31
	s_lshr_b32 s5, s5, 2
	s_add_i32 s5, s5, s6
	v_mov_b32_e32 v193, v234
	s_add_i32 s22, s22, s12
	s_mul_i32 s5, s5, 22
	s_sub_i32 s4, s4, s5
	v_ashrrev_i32_e32 v52, 3, v193
	v_add_u32_e32 v0, s22, v52
	s_lshl_b32 s6, s4, 8
	v_ashrrev_i32_e32 v1, 31, v0
	v_readlane_b32 s4, v252, 20
	v_lshlrev_b64 v[0:1], 11, v[0:1]
	v_add_u32_e32 v2, s6, v52
	v_lshlrev_b32_e32 v190, 4, v193
	v_readlane_b32 s5, v252, 21
	v_ashrrev_i32_e32 v3, 31, v2
	v_and_b32_e32 v200, 0x70, v190
	v_lshl_add_u64 v[0:1], s[4:5], 0, v[0:1]
	v_lshlrev_b64 v[32:33], 11, v[2:3]
	v_lshl_add_u64 v[36:37], v[0:1], 0, v[200:201]
	v_lshl_add_u64 v[2:3], s[2:3], 0, v[32:33]
	v_add_co_u32_e32 v38, vcc, s25, v36
	v_lshl_add_u64 v[34:35], v[2:3], 0, v[200:201]
	s_nop 0
	v_addc_co_u32_e32 v39, vcc, 0, v37, vcc
	v_add_co_u32_e32 v40, vcc, s25, v34
	v_ashrrev_i32_e32 v18, 7, v193
	s_nop 0
	v_addc_co_u32_e32 v41, vcc, 0, v35, vcc
	s_movk_i32 s0, 0x1600
	v_add_co_u32_e32 v42, vcc, s47, v36
	v_mul_lo_u32 v16, v18, s0
	s_nop 0
	v_addc_co_u32_e32 v43, vcc, 0, v37, vcc
	v_ashrrev_i32_e32 v17, 31, v16
	v_lshl_add_u64 v[16:17], v[16:17], 2, s[38:39]
	v_cmp_gt_i32_e32 vcc, 3, v18
	v_mov_b32_e32 v18, s40
	v_mov_b32_e32 v19, s41
	v_cndmask_b32_e32 v16, v18, v16, vcc
	v_lshlrev_b32_e32 v18, 1, v193
	v_cndmask_b32_e32 v17, v19, v17, vcc
	v_and_b32_e32 v19, 0xc0, v18
	v_or_b32_e32 v19, s6, v19
	v_and_b32_e32 v18, 30, v18
	v_bfe_i32 v20, v193, 4, 1
	s_movk_i32 s0, 0xb00
	v_ashrrev_i32_e32 v19, 1, v19
	v_and_or_b32 v18, v20, s0, v18
	v_add_u32_e32 v18, v18, v19
	v_ashrrev_i32_e32 v19, 31, v18
	v_lshl_add_u64 v[16:17], v[18:19], 2, v[16:17]
	v_add_co_u32_e32 v46, vcc, s47, v34
	global_load_dwordx4 v[0:3], v[36:37], off
	global_load_dwordx4 v[4:7], v[34:35], off
	global_load_dwordx4 v[8:11], v[38:39], off
	global_load_dwordx4 v[12:15], v[40:41], off
	global_load_dwordx2 v[44:45], v[16:17], off
	v_addc_co_u32_e32 v47, vcc, 0, v35, vcc
	s_mov_b32 s1, 0x60000
	v_add_co_u32_e32 v48, vcc, s1, v36
	global_load_dwordx4 v[16:19], v[42:43], off
	global_load_dwordx4 v[20:23], v[46:47], off
	v_addc_co_u32_e32 v49, vcc, 0, v37, vcc
	v_add_co_u32_e32 v50, vcc, s1, v34
	v_lshlrev_b32_e32 v53, 5, v52
	s_nop 0
	v_addc_co_u32_e32 v51, vcc, 0, v35, vcc
	global_load_dwordx4 v[24:27], v[48:49], off
	global_load_dwordx4 v[28:31], v[50:51], off
	v_and_b32_e32 v54, 0x80, v52
	v_lshrrev_b32_e32 v55, 2, v52
	v_and_b32_e32 v53, 0x60, v53
	v_and_or_b32 v54, v55, 31, v54
	v_or_b32_e32 v55, v54, v53
	v_mad_u32_u24 v194, v55, s24, v200
	v_add_u32_e32 v55, 64, v52
	s_movk_i32 s1, 0x80
	v_and_b32_e32 v56, 0x80, v55
	v_bfe_u32 v55, v55, 2, 5
	v_bitop3_b32 v54, v54, s1, v53 bitop3:0x36
	v_or3_b32 v55, v56, v55, v53
	v_mad_u32_u24 v196, v54, s24, v200
	v_add_u32_e32 v54, 0xc0, v52
	v_mad_u32_u24 v195, v55, s24, v200
	v_and_b32_e32 v55, 0x80, v54
	v_bfe_u32 v54, v54, 2, 5
	v_or3_b32 v53, v55, v54, v53
	v_mad_u32_u24 v197, v53, s24, v200
	v_lshl_add_u32 v53, v193, 3, 0
	s_and_b32 s4, s51, 7
	v_add_u32_e32 v53, 0x24000, v53
	s_lshl_b32 s13, s4, 8
	v_mad_u64_u32 v[184:185], s[4:5], v52, s24, v[200:201]
	v_readfirstlane_b32 s7, v193
	s_ashr_i32 s34, s7, 6
	s_lshl_b32 s4, s34, 7
	v_and_b32_e32 v191, 31, v193
	s_and_b32 s36, s4, 0x80
	s_ashr_i32 s17, s7, 1
	s_and_b32 s7, s17, 0xffffffc0
	s_or_b32 s4, s13, s12
	s_add_i32 s4, s4, s15
	v_bfe_u32 v192, v193, 5, 1
	v_or_b32_e32 v32, v32, v200
	s_mov_b32 s0, 0x60000
	s_mov_b32 s16, 2
	s_mov_b32 s35, 0
	v_lshlrev_b32_e32 v198, 4, v192
	v_lshl_add_u64 v[186:187], s[30:31], 0, v[32:33]
	s_waitcnt vmcnt(4)
	ds_write_b64 v53, v[44:45]
	v_add_u32_e32 v45, 0, v194
	v_add_u32_e32 v44, 0, v184
	ds_write_b128 v45, v[0:3]
	ds_write_b128 v44, v[4:7] offset:36864
	v_add_u32_e32 v0, 0, v195
	ds_write_b128 v0, v[8:11]
	ds_write_b128 v44, v[12:15] offset:46080
	v_add_u32_e32 v0, 0, v196
	s_waitcnt vmcnt(3)
	ds_write_b128 v0, v[16:19]
	s_waitcnt vmcnt(2)
	ds_write_b128 v44, v[20:23] offset:55296
	v_add_u32_e32 v0, 0, v197
	s_waitcnt vmcnt(1)
	ds_write_b128 v0, v[24:27]
	s_waitcnt vmcnt(0)
	ds_write_b128 v44, v[28:31] offset:64512
	s_waitcnt lgkmcnt(0)
	s_barrier
	global_load_dwordx4 v[128:131], v[36:37], off offset:128
	global_load_dwordx4 v[132:135], v[34:35], off offset:128
	global_load_dwordx4 v[136:139], v[38:39], off offset:128
	global_load_dwordx4 v[140:143], v[40:41], off offset:128
	global_load_dwordx4 v[144:147], v[42:43], off offset:128
	global_load_dwordx4 v[148:151], v[46:47], off offset:128
	global_load_dwordx4 v[152:155], v[48:49], off offset:128
	global_load_dwordx4 v[156:159], v[50:51], off offset:128
	v_or_b32_e32 v0, s36, v191
	v_mul_u32_u24_e32 v185, 0x90, v0
	v_or_b32_e32 v0, s7, v191
	v_mul_lo_u32 v199, v0, s24
	v_add_u32_e32 v0, s4, v52
	v_ashrrev_i32_e32 v1, 31, v0
	v_lshlrev_b64 v[0:1], 11, v[0:1]
	v_or_b32_e32 v0, v0, v200
	v_lshl_add_u64 v[188:189], s[10:11], 0, v[0:1]
	v_mov_b32_e32 v0, 0
	s_mov_b64 s[4:5], 0
	v_mov_b32_e32 v1, v0
	v_mov_b32_e32 v2, v0
	v_mov_b32_e32 v3, v0
	v_mov_b32_e32 v4, v0
	v_mov_b32_e32 v5, v0
	v_mov_b32_e32 v6, v0
	v_mov_b32_e32 v7, v0
	v_mov_b32_e32 v8, v0
	v_mov_b32_e32 v9, v0
	v_mov_b32_e32 v10, v0
	v_mov_b32_e32 v11, v0
	v_mov_b32_e32 v12, v0
	v_mov_b32_e32 v13, v0
	v_mov_b32_e32 v14, v0
	v_mov_b32_e32 v15, v0
	v_mov_b32_e32 v16, v0
	v_mov_b32_e32 v17, v0
	v_mov_b32_e32 v18, v0
	v_mov_b32_e32 v19, v0
	v_mov_b32_e32 v20, v0
	v_mov_b32_e32 v21, v0
	v_mov_b32_e32 v22, v0
	v_mov_b32_e32 v23, v0
	v_mov_b32_e32 v24, v0
	v_mov_b32_e32 v25, v0
	v_mov_b32_e32 v26, v0
	v_mov_b32_e32 v27, v0
	v_mov_b32_e32 v28, v0
	v_mov_b32_e32 v29, v0
	v_mov_b32_e32 v30, v0
	v_mov_b32_e32 v31, v0
	v_mov_b32_e32 v32, v0
	v_mov_b32_e32 v33, v0
	v_mov_b32_e32 v34, v0
	v_mov_b32_e32 v35, v0
	v_mov_b32_e32 v36, v0
	v_mov_b32_e32 v37, v0
	v_mov_b32_e32 v38, v0
	v_mov_b32_e32 v39, v0
	v_mov_b32_e32 v40, v0
	v_mov_b32_e32 v41, v0
	v_mov_b32_e32 v42, v0
	v_mov_b32_e32 v43, v0
	v_mov_b32_e32 v44, v0
	v_mov_b32_e32 v45, v0
	v_mov_b32_e32 v46, v0
	v_mov_b32_e32 v47, v0
	v_mov_b32_e32 v64, v0
	v_mov_b32_e32 v65, v0
	v_mov_b32_e32 v66, v0
	v_mov_b32_e32 v67, v0
	v_mov_b32_e32 v68, v0
	v_mov_b32_e32 v69, v0
	v_mov_b32_e32 v70, v0
	v_mov_b32_e32 v71, v0
	v_mov_b32_e32 v72, v0
	v_mov_b32_e32 v73, v0
	v_mov_b32_e32 v74, v0
	v_mov_b32_e32 v75, v0
	v_mov_b32_e32 v76, v0
	v_mov_b32_e32 v77, v0
	v_mov_b32_e32 v78, v0
	v_mov_b32_e32 v79, v0
	v_mov_b32_e32 v48, v0
	v_mov_b32_e32 v49, v0
	v_mov_b32_e32 v50, v0
	v_mov_b32_e32 v51, v0
	v_mov_b32_e32 v52, v0
	v_mov_b32_e32 v53, v0
	v_mov_b32_e32 v54, v0
	v_mov_b32_e32 v55, v0
	v_mov_b32_e32 v56, v0
	v_mov_b32_e32 v57, v0
	v_mov_b32_e32 v58, v0
	v_mov_b32_e32 v59, v0
	v_mov_b32_e32 v60, v0
	v_mov_b32_e32 v61, v0
	v_mov_b32_e32 v62, v0
	v_mov_b32_e32 v63, v0
	v_mov_b32_e32 v80, v0
	v_mov_b32_e32 v81, v0
	v_mov_b32_e32 v82, v0
	v_mov_b32_e32 v83, v0
	v_mov_b32_e32 v84, v0
	v_mov_b32_e32 v85, v0
	v_mov_b32_e32 v86, v0
	v_mov_b32_e32 v87, v0
	v_mov_b32_e32 v88, v0
	v_mov_b32_e32 v89, v0
	v_mov_b32_e32 v90, v0
	v_mov_b32_e32 v91, v0
	v_mov_b32_e32 v92, v0
	v_mov_b32_e32 v93, v0
	v_mov_b32_e32 v94, v0
	v_mov_b32_e32 v95, v0
	v_mov_b32_e32 v96, v0
	v_mov_b32_e32 v97, v0
	v_mov_b32_e32 v98, v0
	v_mov_b32_e32 v99, v0
	v_mov_b32_e32 v100, v0
	v_mov_b32_e32 v101, v0
	v_mov_b32_e32 v102, v0
	v_mov_b32_e32 v103, v0
	v_mov_b32_e32 v104, v0
	v_mov_b32_e32 v105, v0
	v_mov_b32_e32 v106, v0
	v_mov_b32_e32 v107, v0
	v_mov_b32_e32 v108, v0
	v_mov_b32_e32 v109, v0
	v_mov_b32_e32 v110, v0
	v_mov_b32_e32 v111, v0
	v_mov_b32_e32 v112, v0
	v_mov_b32_e32 v113, v0
	v_mov_b32_e32 v114, v0
	v_mov_b32_e32 v115, v0
	v_mov_b32_e32 v116, v0
	v_mov_b32_e32 v117, v0
	v_mov_b32_e32 v118, v0
	v_mov_b32_e32 v119, v0
	v_mov_b32_e32 v120, v0
	v_mov_b32_e32 v121, v0
	v_mov_b32_e32 v122, v0
	v_mov_b32_e32 v123, v0
	v_mov_b32_e32 v124, v0
	v_mov_b32_e32 v125, v0
	v_mov_b32_e32 v126, v0
	v_mov_b32_e32 v127, v0
	v_readfirstlane_b32 s92, v188
	v_readfirstlane_b32 s93, v189
	v_readfirstlane_b32 s94, v186
	v_readfirstlane_b32 s95, v187
	s_nop 1
	v_subrev_u32_e32 v248, s92, v188
	v_add_u32_e32 v249, 0x20000, v248
	v_add_u32_e32 v250, 0x40000, v248
	v_add_u32_e32 v251, 0x60000, v248
	s_add_u32 s92, s92, 0x6d00000
	s_addc_u32 s93, s93, 0
	s_add_u32 s94, s94, 0x900000
	s_addc_u32 s95, s95, 0
	s_branch .LBB0_758

.LBB0_758:
	s_add_i32 s12, s16, -2
	s_and_b32 s12, s12, 2
	s_mul_i32 s12, s12, 0x9000
	s_add_i32 s12, s12, 0
	v_add3_u32 v200, s12, v199, v198
	ds_read_b128 v[160:163], v200 offset:36864
	v_add3_u32 v218, s12, v185, v198
	ds_read_b128 v[164:167], v218
	ds_read_b128 v[168:171], v218 offset:4608
	ds_read_b128 v[172:175], v218 offset:9216
	ds_read_b128 v[176:179], v218 offset:13824
	s_cmpk_eq_i32 s4, 0x780
	s_waitcnt lgkmcnt(3)
	v_mfma_f32_32x32x16_bf16 v[112:127], v[160:163], v[164:167], v[112:127]
	s_waitcnt lgkmcnt(2)
	v_mfma_f32_32x32x16_bf16 v[96:111], v[160:163], v[168:171], v[96:111]
	s_waitcnt lgkmcnt(1)
	v_mfma_f32_32x32x16_bf16 v[80:95], v[160:163], v[172:175], v[80:95]
	s_waitcnt lgkmcnt(0)
	v_mfma_f32_32x32x16_bf16 v[48:63], v[160:163], v[176:179], v[48:63]
	ds_read_b128 v[160:163], v200 offset:41472
	s_waitcnt lgkmcnt(0)
	v_mfma_f32_32x32x16_bf16 v[64:79], v[160:163], v[164:167], v[64:79]
	v_mfma_f32_32x32x16_bf16 v[32:47], v[160:163], v[168:171], v[32:47]
	v_mfma_f32_32x32x16_bf16 v[16:31], v[160:163], v[172:175], v[16:31]
	ds_read_b128 v[164:167], v200 offset:36896
	ds_read_b128 v[168:171], v218 offset:32
	ds_read_b128 v[172:175], v218 offset:4640
	ds_read_b128 v[180:183], v218 offset:9248
	ds_read_b128 v[202:205], v218 offset:13856
	ds_read_b128 v[206:209], v200 offset:41504
	v_mfma_f32_32x32x16_bf16 v[0:15], v[160:163], v[176:179], v[0:15]
	s_waitcnt lgkmcnt(4)
	v_mfma_f32_32x32x16_bf16 v[112:127], v[164:167], v[168:171], v[112:127]
	s_waitcnt lgkmcnt(3)
	v_mfma_f32_32x32x16_bf16 v[96:111], v[164:167], v[172:175], v[96:111]
	s_waitcnt lgkmcnt(2)
	v_mfma_f32_32x32x16_bf16 v[80:95], v[164:167], v[180:183], v[80:95]
	s_waitcnt lgkmcnt(1)
	v_mfma_f32_32x32x16_bf16 v[48:63], v[164:167], v[202:205], v[48:63]
	s_waitcnt lgkmcnt(0)
	v_mfma_f32_32x32x16_bf16 v[64:79], v[206:209], v[168:171], v[64:79]
	v_mfma_f32_32x32x16_bf16 v[32:47], v[206:209], v[172:175], v[32:47]
	ds_read_b128 v[160:163], v200 offset:36928
	ds_read_b128 v[210:213], v200 offset:41536
	ds_read_b128 v[164:167], v218 offset:64
	ds_read_b128 v[168:171], v218 offset:4672
	ds_read_b128 v[172:175], v218 offset:9280
	ds_read_b128 v[214:217], v218 offset:13888
	v_mfma_f32_32x32x16_bf16 v[16:31], v[206:209], v[180:183], v[16:31]
	v_mfma_f32_32x32x16_bf16 v[0:15], v[206:209], v[202:205], v[0:15]
	s_waitcnt lgkmcnt(3)
	v_mfma_f32_32x32x16_bf16 v[112:127], v[160:163], v[164:167], v[112:127]
	s_waitcnt lgkmcnt(2)
	v_mfma_f32_32x32x16_bf16 v[96:111], v[160:163], v[168:171], v[96:111]
	s_waitcnt lgkmcnt(1)
	v_mfma_f32_32x32x16_bf16 v[80:95], v[160:163], v[172:175], v[80:95]
	s_waitcnt lgkmcnt(0)
	v_mfma_f32_32x32x16_bf16 v[48:63], v[160:163], v[214:217], v[48:63]
	v_mfma_f32_32x32x16_bf16 v[64:79], v[210:213], v[164:167], v[64:79]
	v_mfma_f32_32x32x16_bf16 v[32:47], v[210:213], v[168:171], v[32:47]
	v_mfma_f32_32x32x16_bf16 v[16:31], v[210:213], v[172:175], v[16:31]
	ds_read_b128 v[176:179], v200 offset:36960
	ds_read_b128 v[160:163], v200 offset:41568
	ds_read_b128 v[180:183], v218 offset:96
	ds_read_b128 v[172:175], v218 offset:4704
	ds_read_b128 v[168:171], v218 offset:9312
	ds_read_b128 v[164:167], v218 offset:13920
	v_mfma_f32_32x32x16_bf16 v[0:15], v[210:213], v[214:217], v[0:15]
	s_cbranch_scc1 .LBB0_757
	s_and_b32 s12, s16, 2
	s_mul_i32 s12, s12, 0x9000
	s_add_i32 s12, s12, 0
	v_add_u32_e32 v202, s12, v194
	v_add_u32_e32 v200, s12, v184
	s_waitcnt vmcnt(7)
	ds_write_b128 v202, v[128:131]
	s_waitcnt vmcnt(6)
	ds_write_b128 v200, v[132:135] offset:36864
	v_add_u32_e32 v202, s12, v195
	s_waitcnt vmcnt(5)
	ds_write_b128 v202, v[136:139]
	s_waitcnt vmcnt(4)
	ds_write_b128 v200, v[140:143] offset:46080
	v_add_u32_e32 v202, s12, v196
	s_cmp_gt_u32 s35, 13
	s_waitcnt vmcnt(3)
	ds_write_b128 v202, v[144:147]
	s_waitcnt vmcnt(2)
	ds_write_b128 v200, v[148:151] offset:55296
	v_add_u32_e32 v202, s12, v197
	s_waitcnt vmcnt(1)
	ds_write_b128 v202, v[152:155]
	s_waitcnt vmcnt(0)
	ds_write_b128 v200, v[156:159] offset:64512
	s_cbranch_scc1 .LBB0_756
	s_add_u32 s96, s92, s4
	s_addc_u32 s97, s93, s5
	s_add_u32 s98, s94, s4
	s_addc_u32 s99, s95, s5
	global_load_dwordx4 v[128:131], v248, s[96:97] offset:256
	global_load_dwordx4 v[132:135], v248, s[98:99] offset:256
	global_load_dwordx4 v[136:139], v249, s[96:97] offset:256
	global_load_dwordx4 v[140:143], v249, s[98:99] offset:256
	global_load_dwordx4 v[144:147], v250, s[96:97] offset:256
	global_load_dwordx4 v[148:151], v250, s[98:99] offset:256
	global_load_dwordx4 v[152:155], v251, s[96:97] offset:256
	global_load_dwordx4 v[156:159], v251, s[98:99] offset:256
	s_branch .LBB0_756

.LBB0_796:
	s_and_b32 s4, s16, 7
	v_readlane_b32 s5, v253, 25
	s_or_b32 s4, s4, s5
	s_ashr_i32 s5, s16, 31
	s_lshr_b32 s5, s5, 27
	s_add_i32 s5, s16, s5
	s_lshl_b32 s6, s4, 8
	s_ashr_i32 s4, s16, 3
	s_lshl_b32 s5, s5, 6
	s_lshr_b32 s7, s4, 30
	s_and_b32 s5, s5, 0xfffff800
	s_add_i32 s7, s4, s7
	v_mov_b32_e32 v185, v234
	s_add_i32 s6, s6, s5
	s_and_b32 s7, s7, 0xfffffc
	s_sub_i32 s4, s4, s7
	v_ashrrev_i32_e32 v50, 3, v185
	v_add_u32_e32 v0, s6, v50
	s_lshl_b32 s7, s4, 8
	v_ashrrev_i32_e32 v1, 31, v0
	v_readlane_b32 s12, v253, 18
	v_and_b32_e32 v51, 7, v185
	v_lshlrev_b64 v[0:1], 9, v[0:1]
	v_add_u32_e32 v2, s7, v50
	v_readlane_b32 s13, v253, 19
	v_ashrrev_i32_e32 v3, 31, v2
	v_lshlrev_b32_e32 v200, 4, v51
	v_lshl_add_u64 v[0:1], s[12:13], 0, v[0:1]
	v_lshlrev_b64 v[32:33], 9, v[2:3]
	v_lshl_add_u64 v[34:35], v[0:1], 0, v[200:201]
	s_mov_b32 s0, 0x8000
	v_lshl_add_u64 v[2:3], s[2:3], 0, v[32:33]
	v_add_co_u32_e32 v38, vcc, s0, v34
	v_lshl_add_u64 v[36:37], v[2:3], 0, v[200:201]
	s_nop 0
	v_addc_co_u32_e32 v39, vcc, 0, v35, vcc
	v_add_co_u32_e32 v40, vcc, s0, v36
	s_mov_b32 s0, 0x10000
	s_nop 0
	v_addc_co_u32_e32 v41, vcc, 0, v37, vcc
	v_add_co_u32_e32 v42, vcc, s0, v34
	global_load_dwordx4 v[0:3], v[34:35], off
	global_load_dwordx4 v[4:7], v[36:37], off
	v_addc_co_u32_e32 v43, vcc, 0, v35, vcc
	v_add_co_u32_e32 v44, vcc, s0, v36
	s_mov_b32 s0, 0x18000
	s_nop 0
	v_addc_co_u32_e32 v45, vcc, 0, v37, vcc
	v_add_co_u32_e32 v46, vcc, s0, v34
	global_load_dwordx4 v[8:11], v[38:39], off
	global_load_dwordx4 v[12:15], v[40:41], off
	v_addc_co_u32_e32 v47, vcc, 0, v35, vcc
	v_add_co_u32_e32 v48, vcc, s0, v36
	global_load_dwordx4 v[16:19], v[42:43], off
	global_load_dwordx4 v[20:23], v[44:45], off
	v_addc_co_u32_e32 v49, vcc, 0, v37, vcc
	global_load_dwordx4 v[24:27], v[46:47], off
	global_load_dwordx4 v[28:31], v[48:49], off
	v_lshlrev_b32_e32 v184, 3, v51
	v_mul_lo_u32 v51, v50, s24
	v_add3_u32 v192, v51, v200, 0
	v_readfirstlane_b32 s12, v185
	s_ashr_i32 s22, s12, 6
	s_and_b32 s4, s14, 7
	s_lshl_b32 s13, s22, 7
	s_lshl_b32 s4, s4, 8
	v_and_b32_e32 v190, 31, v185
	s_and_b32 s34, s13, 0x80
	s_ashr_i32 s35, s12, 1
	s_andn2_b32 s35, s35, 63
	s_or_b32 s4, s4, s5
	s_add_i32 s4, s4, s15
	v_bfe_u32 v191, v185, 5, 1
	v_or_b32_e32 v32, v32, v200
	s_mov_b32 s17, 0
	v_lshlrev_b32_e32 v194, 4, v191
	v_lshl_add_u64 v[186:187], s[30:31], 0, v[32:33]
	s_mov_b32 s36, 2
	s_waitcnt vmcnt(7)
	ds_write_b128 v192, v[0:3]
	s_waitcnt vmcnt(6)
	ds_write_b128 v192, v[4:7] offset:36864
	s_waitcnt vmcnt(5)
	ds_write_b128 v192, v[8:11] offset:9216
	s_waitcnt vmcnt(4)
	ds_write_b128 v192, v[12:15] offset:46080
	s_waitcnt vmcnt(3)
	ds_write_b128 v192, v[16:19] offset:18432
	s_waitcnt vmcnt(2)
	ds_write_b128 v192, v[20:23] offset:55296
	s_waitcnt vmcnt(1)
	ds_write_b128 v192, v[24:27] offset:27648
	s_waitcnt vmcnt(0)
	ds_write_b128 v192, v[28:31] offset:64512
	s_waitcnt lgkmcnt(0)
	s_barrier
	global_load_dwordx4 v[128:131], v[34:35], off offset:128
	global_load_dwordx4 v[132:135], v[36:37], off offset:128
	global_load_dwordx4 v[136:139], v[38:39], off offset:128
	global_load_dwordx4 v[140:143], v[40:41], off offset:128
	global_load_dwordx4 v[144:147], v[42:43], off offset:128
	global_load_dwordx4 v[148:151], v[44:45], off offset:128
	global_load_dwordx4 v[152:155], v[46:47], off offset:128
	global_load_dwordx4 v[156:159], v[48:49], off offset:128
	v_or_b32_e32 v0, s34, v190
	v_mul_u32_u24_e32 v193, 0x90, v0
	v_or_b32_e32 v0, s35, v190
	v_mul_lo_u32 v195, v0, s24
	v_add_u32_e32 v0, s4, v50
	v_ashrrev_i32_e32 v1, 31, v0
	v_lshlrev_b64 v[0:1], 9, v[0:1]
	v_or_b32_e32 v0, v0, v200
	v_lshl_add_u64 v[188:189], s[10:11], 0, v[0:1]
	v_mov_b32_e32 v0, 0
	s_mov_b64 s[4:5], 0
	v_mov_b32_e32 v1, v0
	v_mov_b32_e32 v2, v0
	v_mov_b32_e32 v3, v0
	v_mov_b32_e32 v4, v0
	v_mov_b32_e32 v5, v0
	v_mov_b32_e32 v6, v0
	v_mov_b32_e32 v7, v0
	v_mov_b32_e32 v8, v0
	v_mov_b32_e32 v9, v0
	v_mov_b32_e32 v10, v0
	v_mov_b32_e32 v11, v0
	v_mov_b32_e32 v12, v0
	v_mov_b32_e32 v13, v0
	v_mov_b32_e32 v14, v0
	v_mov_b32_e32 v15, v0
	v_mov_b32_e32 v16, v0
	v_mov_b32_e32 v17, v0
	v_mov_b32_e32 v18, v0
	v_mov_b32_e32 v19, v0
	v_mov_b32_e32 v20, v0
	v_mov_b32_e32 v21, v0
	v_mov_b32_e32 v22, v0
	v_mov_b32_e32 v23, v0
	v_mov_b32_e32 v24, v0
	v_mov_b32_e32 v25, v0
	v_mov_b32_e32 v26, v0
	v_mov_b32_e32 v27, v0
	v_mov_b32_e32 v28, v0
	v_mov_b32_e32 v29, v0
	v_mov_b32_e32 v30, v0
	v_mov_b32_e32 v31, v0
	v_mov_b32_e32 v48, v0
	v_mov_b32_e32 v49, v0
	v_mov_b32_e32 v50, v0
	v_mov_b32_e32 v51, v0
	v_mov_b32_e32 v52, v0
	v_mov_b32_e32 v53, v0
	v_mov_b32_e32 v54, v0
	v_mov_b32_e32 v55, v0
	v_mov_b32_e32 v56, v0
	v_mov_b32_e32 v57, v0
	v_mov_b32_e32 v58, v0
	v_mov_b32_e32 v59, v0
	v_mov_b32_e32 v60, v0
	v_mov_b32_e32 v61, v0
	v_mov_b32_e32 v62, v0
	v_mov_b32_e32 v63, v0
	v_mov_b32_e32 v80, v0
	v_mov_b32_e32 v81, v0
	v_mov_b32_e32 v82, v0
	v_mov_b32_e32 v83, v0
	v_mov_b32_e32 v84, v0
	v_mov_b32_e32 v85, v0
	v_mov_b32_e32 v86, v0
	v_mov_b32_e32 v87, v0
	v_mov_b32_e32 v88, v0
	v_mov_b32_e32 v89, v0
	v_mov_b32_e32 v90, v0
	v_mov_b32_e32 v91, v0
	v_mov_b32_e32 v92, v0
	v_mov_b32_e32 v93, v0
	v_mov_b32_e32 v94, v0
	v_mov_b32_e32 v95, v0
	v_mov_b32_e32 v32, v0
	v_mov_b32_e32 v33, v0
	v_mov_b32_e32 v34, v0
	v_mov_b32_e32 v35, v0
	v_mov_b32_e32 v36, v0
	v_mov_b32_e32 v37, v0
	v_mov_b32_e32 v38, v0
	v_mov_b32_e32 v39, v0
	v_mov_b32_e32 v40, v0
	v_mov_b32_e32 v41, v0
	v_mov_b32_e32 v42, v0
	v_mov_b32_e32 v43, v0
	v_mov_b32_e32 v44, v0
	v_mov_b32_e32 v45, v0
	v_mov_b32_e32 v46, v0
	v_mov_b32_e32 v47, v0
	v_mov_b32_e32 v64, v0
	v_mov_b32_e32 v65, v0
	v_mov_b32_e32 v66, v0
	v_mov_b32_e32 v67, v0
	v_mov_b32_e32 v68, v0
	v_mov_b32_e32 v69, v0
	v_mov_b32_e32 v70, v0
	v_mov_b32_e32 v71, v0
	v_mov_b32_e32 v72, v0
	v_mov_b32_e32 v73, v0
	v_mov_b32_e32 v74, v0
	v_mov_b32_e32 v75, v0
	v_mov_b32_e32 v76, v0
	v_mov_b32_e32 v77, v0
	v_mov_b32_e32 v78, v0
	v_mov_b32_e32 v79, v0
	v_mov_b32_e32 v96, v0
	v_mov_b32_e32 v97, v0
	v_mov_b32_e32 v98, v0
	v_mov_b32_e32 v99, v0
	v_mov_b32_e32 v100, v0
	v_mov_b32_e32 v101, v0
	v_mov_b32_e32 v102, v0
	v_mov_b32_e32 v103, v0
	v_mov_b32_e32 v104, v0
	v_mov_b32_e32 v105, v0
	v_mov_b32_e32 v106, v0
	v_mov_b32_e32 v107, v0
	v_mov_b32_e32 v108, v0
	v_mov_b32_e32 v109, v0
	v_mov_b32_e32 v110, v0
	v_mov_b32_e32 v111, v0
	v_mov_b32_e32 v112, v0
	v_mov_b32_e32 v113, v0
	v_mov_b32_e32 v114, v0
	v_mov_b32_e32 v115, v0
	v_mov_b32_e32 v116, v0
	v_mov_b32_e32 v117, v0
	v_mov_b32_e32 v118, v0
	v_mov_b32_e32 v119, v0
	v_mov_b32_e32 v120, v0
	v_mov_b32_e32 v121, v0
	v_mov_b32_e32 v122, v0
	v_mov_b32_e32 v123, v0
	v_mov_b32_e32 v124, v0
	v_mov_b32_e32 v125, v0
	v_mov_b32_e32 v126, v0
	v_mov_b32_e32 v127, v0
	v_readfirstlane_b32 s92, v188
	v_readfirstlane_b32 s93, v189
	v_readfirstlane_b32 s94, v186
	v_readfirstlane_b32 s95, v187
	s_nop 1
	v_subrev_u32_e32 v248, s92, v188
	v_add_u32_e32 v249, 0x8000, v248
	v_add_u32_e32 v250, 0x10000, v248
	v_add_u32_e32 v251, 0x18000, v248
	s_add_u32 s92, s92, 0x1c300000
	s_addc_u32 s93, s93, 0
	s_add_u32 s94, s94, 0x1b80000
	s_addc_u32 s95, s95, 0
	s_branch .LBB0_799

.LBB0_799:
	s_add_i32 s12, s36, -2
	s_and_b32 s12, s12, 2
	s_mul_i32 s12, s12, 0x9000
	s_add_i32 s12, s12, 0
	v_add3_u32 v214, s12, v195, v194
	ds_read_b128 v[160:163], v214 offset:36864
	v_add3_u32 v215, s12, v193, v194
	ds_read_b128 v[164:167], v215
	ds_read_b128 v[168:171], v215 offset:4608
	ds_read_b128 v[172:175], v215 offset:9216
	ds_read_b128 v[176:179], v215 offset:13824
	s_cmpk_eq_i32 s4, 0x180
	s_waitcnt lgkmcnt(3)
	v_mfma_f32_32x32x16_bf16 v[112:127], v[160:163], v[164:167], v[112:127]
	s_waitcnt lgkmcnt(2)
	v_mfma_f32_32x32x16_bf16 v[96:111], v[160:163], v[168:171], v[96:111]
	s_waitcnt lgkmcnt(1)
	v_mfma_f32_32x32x16_bf16 v[64:79], v[160:163], v[172:175], v[64:79]
	s_waitcnt lgkmcnt(0)
	v_mfma_f32_32x32x16_bf16 v[32:47], v[160:163], v[176:179], v[32:47]
	ds_read_b128 v[160:163], v214 offset:41472
	s_waitcnt lgkmcnt(0)
	v_mfma_f32_32x32x16_bf16 v[80:95], v[160:163], v[164:167], v[80:95]
	v_mfma_f32_32x32x16_bf16 v[48:63], v[160:163], v[168:171], v[48:63]
	v_mfma_f32_32x32x16_bf16 v[16:31], v[160:163], v[172:175], v[16:31]
	ds_read_b128 v[164:167], v214 offset:36896
	ds_read_b128 v[168:171], v215 offset:32
	ds_read_b128 v[172:175], v215 offset:4640
	ds_read_b128 v[180:183], v215 offset:9248
	ds_read_b128 v[196:199], v215 offset:13856
	ds_read_b128 v[202:205], v214 offset:41504
	v_mfma_f32_32x32x16_bf16 v[0:15], v[160:163], v[176:179], v[0:15]
	s_waitcnt lgkmcnt(4)
	v_mfma_f32_32x32x16_bf16 v[112:127], v[164:167], v[168:171], v[112:127]
	s_waitcnt lgkmcnt(3)
	v_mfma_f32_32x32x16_bf16 v[96:111], v[164:167], v[172:175], v[96:111]
	s_waitcnt lgkmcnt(2)
	v_mfma_f32_32x32x16_bf16 v[64:79], v[164:167], v[180:183], v[64:79]
	s_waitcnt lgkmcnt(1)
	v_mfma_f32_32x32x16_bf16 v[32:47], v[164:167], v[196:199], v[32:47]
	s_waitcnt lgkmcnt(0)
	v_mfma_f32_32x32x16_bf16 v[80:95], v[202:205], v[168:171], v[80:95]
	v_mfma_f32_32x32x16_bf16 v[48:63], v[202:205], v[172:175], v[48:63]
	ds_read_b128 v[160:163], v214 offset:36928
	ds_read_b128 v[206:209], v214 offset:41536
	ds_read_b128 v[164:167], v215 offset:64
	ds_read_b128 v[168:171], v215 offset:4672
	ds_read_b128 v[172:175], v215 offset:9280
	ds_read_b128 v[210:213], v215 offset:13888
	v_mfma_f32_32x32x16_bf16 v[16:31], v[202:205], v[180:183], v[16:31]
	v_mfma_f32_32x32x16_bf16 v[0:15], v[202:205], v[196:199], v[0:15]
	s_waitcnt lgkmcnt(3)
	v_mfma_f32_32x32x16_bf16 v[112:127], v[160:163], v[164:167], v[112:127]
	s_waitcnt lgkmcnt(2)
	v_mfma_f32_32x32x16_bf16 v[96:111], v[160:163], v[168:171], v[96:111]
	s_waitcnt lgkmcnt(1)
	v_mfma_f32_32x32x16_bf16 v[64:79], v[160:163], v[172:175], v[64:79]
	s_waitcnt lgkmcnt(0)
	v_mfma_f32_32x32x16_bf16 v[32:47], v[160:163], v[210:213], v[32:47]
	v_mfma_f32_32x32x16_bf16 v[80:95], v[206:209], v[164:167], v[80:95]
	v_mfma_f32_32x32x16_bf16 v[48:63], v[206:209], v[168:171], v[48:63]
	v_mfma_f32_32x32x16_bf16 v[16:31], v[206:209], v[172:175], v[16:31]
	ds_read_b128 v[176:179], v214 offset:36960
	ds_read_b128 v[160:163], v214 offset:41568
	ds_read_b128 v[180:183], v215 offset:96
	ds_read_b128 v[172:175], v215 offset:4704
	ds_read_b128 v[168:171], v215 offset:9312
	ds_read_b128 v[164:167], v215 offset:13920
	v_mfma_f32_32x32x16_bf16 v[0:15], v[206:209], v[210:213], v[0:15]
	s_cbranch_scc1 .LBB0_798
	s_and_b32 s12, s36, 2
	s_mul_i32 s12, s12, 0x9000
	v_add_u32_e32 v196, s12, v192
	s_cmp_gt_u32 s17, 1
	s_waitcnt vmcnt(7)
	ds_write_b128 v196, v[128:131]
	s_waitcnt vmcnt(6)
	ds_write_b128 v196, v[132:135] offset:36864
	s_waitcnt vmcnt(5)
	ds_write_b128 v196, v[136:139] offset:9216
	s_waitcnt vmcnt(4)
	ds_write_b128 v196, v[140:143] offset:46080
	s_waitcnt vmcnt(3)
	ds_write_b128 v196, v[144:147] offset:18432
	s_waitcnt vmcnt(2)
	ds_write_b128 v196, v[148:151] offset:55296
	s_waitcnt vmcnt(1)
	ds_write_b128 v196, v[152:155] offset:27648
	s_waitcnt vmcnt(0)
	ds_write_b128 v196, v[156:159] offset:64512
	s_cbranch_scc1 .LBB0_797
	s_add_u32 s96, s92, s4
	s_addc_u32 s97, s93, s5
	s_add_u32 s98, s94, s4
	s_addc_u32 s99, s95, s5
	global_load_dwordx4 v[128:131], v248, s[96:97] offset:256
	global_load_dwordx4 v[132:135], v248, s[98:99] offset:256
	global_load_dwordx4 v[136:139], v249, s[96:97] offset:256
	global_load_dwordx4 v[140:143], v249, s[98:99] offset:256
	global_load_dwordx4 v[144:147], v250, s[96:97] offset:256
	global_load_dwordx4 v[148:151], v250, s[98:99] offset:256
	global_load_dwordx4 v[152:155], v251, s[96:97] offset:256
	global_load_dwordx4 v[156:159], v251, s[98:99] offset:256
	s_branch .LBB0_797

.LBB0_955:
	s_and_b32 s2, s17, 7
	v_readlane_b32 s3, v253, 25
	s_or_b32 s2, s2, s3
	s_ashr_i32 s3, s17, 31
	s_lshr_b32 s3, s3, 27
	s_add_i32 s3, s17, s3
	s_lshl_b32 s3, s3, 6
	s_lshl_b32 s22, s2, 8
	s_ashr_i32 s2, s17, 3
	s_and_b32 s6, s3, 0xfffff800
	s_lshr_b32 s3, s2, 30
	s_add_i32 s3, s2, s3
	v_mov_b32_e32 v187, v234
	s_add_i32 s22, s22, s6
	s_and_b32 s3, s3, 0xfffffc
	s_sub_i32 s2, s2, s3
	v_ashrrev_i32_e32 v50, 3, v187
	v_and_b32_e32 v48, 7, v187
	v_add_u32_e32 v4, s22, v50
	s_movk_i32 s1, 0x1600
	v_mov_b64_e32 v[2:3], s[18:19]
	s_lshl_b32 s35, s2, 8
	v_lshlrev_b32_e32 v184, 4, v48
	v_mad_i64_i32 v[2:3], s[2:3], v4, s1, v[2:3]
	v_mov_b32_e32 v185, v201
	v_add_u32_e32 v49, s35, v50
	v_mov_b64_e32 v[0:1], s[4:5]
	v_lshl_add_u64 v[32:33], v[2:3], 0, v[184:185]
	s_mov_b32 s0, 0x58000
	v_mad_i64_i32 v[0:1], s[2:3], v49, s1, v[0:1]
	v_add_co_u32_e32 v36, vcc, s0, v32
	v_lshl_add_u64 v[34:35], v[0:1], 0, v[184:185]
	s_nop 0
	v_addc_co_u32_e32 v37, vcc, 0, v33, vcc
	v_add_co_u32_e32 v38, vcc, s0, v34
	s_mov_b32 s0, 0xb0000
	s_nop 0
	v_addc_co_u32_e32 v39, vcc, 0, v35, vcc
	v_add_co_u32_e32 v40, vcc, s0, v32
	global_load_dwordx4 v[0:3], v[32:33], off
	global_load_dwordx4 v[4:7], v[34:35], off
	v_addc_co_u32_e32 v41, vcc, 0, v33, vcc
	v_add_co_u32_e32 v42, vcc, s0, v34
	s_mov_b32 s0, 0x108000
	s_nop 0
	v_addc_co_u32_e32 v43, vcc, 0, v35, vcc
	v_add_co_u32_e32 v44, vcc, s0, v32
	global_load_dwordx4 v[8:11], v[36:37], off
	global_load_dwordx4 v[12:15], v[38:39], off
	v_addc_co_u32_e32 v45, vcc, 0, v33, vcc
	v_add_co_u32_e32 v46, vcc, s0, v34
	global_load_dwordx4 v[16:19], v[40:41], off
	global_load_dwordx4 v[20:23], v[42:43], off
	v_addc_co_u32_e32 v47, vcc, 0, v35, vcc
	global_load_dwordx4 v[24:27], v[44:45], off
	global_load_dwordx4 v[28:31], v[46:47], off
	v_lshlrev_b32_e32 v186, 3, v48
	v_mul_lo_u32 v48, v50, s24
	v_add3_u32 v193, v48, v184, 0
	s_and_b32 s2, s16, 7
	v_readfirstlane_b32 s12, v187
	s_lshl_b32 s7, s2, 8
	s_ashr_i32 s36, s12, 6
	v_mad_i64_i32 v[48:49], s[2:3], v49, s1, 0
	s_lshl_b32 s2, s36, 7
	v_and_b32_e32 v185, 31, v187
	s_and_b32 s37, s2, 0x80
	s_ashr_i32 s38, s12, 1
	s_andn2_b32 s38, s38, 63
	s_or_b32 s2, s7, s6
	s_add_i32 s2, s2, s15
	v_bfe_u32 v192, v187, 5, 1
	v_or_b32_e32 v48, v48, v184
	s_mov_b32 s34, 0
	v_lshlrev_b32_e32 v200, 4, v192
	v_lshl_add_u64 v[188:189], s[30:31], 0, v[48:49]
	s_mov_b32 s39, 0
	s_waitcnt vmcnt(7)
	ds_write_b128 v193, v[0:3]
	s_waitcnt vmcnt(6)
	ds_write_b128 v193, v[4:7] offset:36864
	s_waitcnt vmcnt(5)
	ds_write_b128 v193, v[8:11] offset:9216
	s_waitcnt vmcnt(4)
	ds_write_b128 v193, v[12:15] offset:46080
	s_waitcnt vmcnt(3)
	ds_write_b128 v193, v[16:19] offset:18432
	s_waitcnt vmcnt(2)
	ds_write_b128 v193, v[20:23] offset:55296
	s_waitcnt vmcnt(1)
	ds_write_b128 v193, v[24:27] offset:27648
	s_waitcnt vmcnt(0)
	ds_write_b128 v193, v[28:31] offset:64512
	s_waitcnt lgkmcnt(0)
	s_barrier
	global_load_dwordx4 v[156:159], v[46:47], off offset:128
	global_load_dwordx4 v[152:155], v[44:45], off offset:128
	global_load_dwordx4 v[148:151], v[42:43], off offset:128
	global_load_dwordx4 v[144:147], v[40:41], off offset:128
	global_load_dwordx4 v[140:143], v[38:39], off offset:128
	global_load_dwordx4 v[136:139], v[36:37], off offset:128
	global_load_dwordx4 v[132:135], v[34:35], off offset:128
	global_load_dwordx4 v[128:131], v[32:33], off offset:128
	v_or_b32_e32 v0, s37, v185
	v_mul_u32_u24_e32 v194, 0x90, v0
	v_or_b32_e32 v0, s38, v185
	v_mul_lo_u32 v195, v0, s24
	v_add_u32_e32 v0, s2, v50
	v_mad_i64_i32 v[0:1], s[2:3], v0, s1, 0
	v_or_b32_e32 v0, v0, v184
	v_lshl_add_u64 v[190:191], s[10:11], 0, v[0:1]
	v_mov_b32_e32 v0, 0
	s_mov_b64 s[2:3], 0
	v_mov_b32_e32 v1, v0
	v_mov_b32_e32 v2, v0
	v_mov_b32_e32 v3, v0
	v_mov_b32_e32 v4, v0
	v_mov_b32_e32 v5, v0
	v_mov_b32_e32 v6, v0
	v_mov_b32_e32 v7, v0
	v_mov_b32_e32 v8, v0
	v_mov_b32_e32 v9, v0
	v_mov_b32_e32 v10, v0
	v_mov_b32_e32 v11, v0
	v_mov_b32_e32 v12, v0
	v_mov_b32_e32 v13, v0
	v_mov_b32_e32 v14, v0
	v_mov_b32_e32 v15, v0
	v_mov_b32_e32 v32, v0
	v_mov_b32_e32 v33, v0
	v_mov_b32_e32 v34, v0
	v_mov_b32_e32 v35, v0
	v_mov_b32_e32 v36, v0
	v_mov_b32_e32 v37, v0
	v_mov_b32_e32 v38, v0
	v_mov_b32_e32 v39, v0
	v_mov_b32_e32 v40, v0
	v_mov_b32_e32 v41, v0
	v_mov_b32_e32 v42, v0
	v_mov_b32_e32 v43, v0
	v_mov_b32_e32 v44, v0
	v_mov_b32_e32 v45, v0
	v_mov_b32_e32 v46, v0
	v_mov_b32_e32 v47, v0
	v_mov_b32_e32 v64, v0
	v_mov_b32_e32 v65, v0
	v_mov_b32_e32 v66, v0
	v_mov_b32_e32 v67, v0
	v_mov_b32_e32 v68, v0
	v_mov_b32_e32 v69, v0
	v_mov_b32_e32 v70, v0
	v_mov_b32_e32 v71, v0
	v_mov_b32_e32 v72, v0
	v_mov_b32_e32 v73, v0
	v_mov_b32_e32 v74, v0
	v_mov_b32_e32 v75, v0
	v_mov_b32_e32 v76, v0
	v_mov_b32_e32 v77, v0
	v_mov_b32_e32 v78, v0
	v_mov_b32_e32 v79, v0
	v_mov_b32_e32 v96, v0
	v_mov_b32_e32 v97, v0
	v_mov_b32_e32 v98, v0
	v_mov_b32_e32 v99, v0
	v_mov_b32_e32 v100, v0
	v_mov_b32_e32 v101, v0
	v_mov_b32_e32 v102, v0
	v_mov_b32_e32 v103, v0
	v_mov_b32_e32 v104, v0
	v_mov_b32_e32 v105, v0
	v_mov_b32_e32 v106, v0
	v_mov_b32_e32 v107, v0
	v_mov_b32_e32 v108, v0
	v_mov_b32_e32 v109, v0
	v_mov_b32_e32 v110, v0
	v_mov_b32_e32 v111, v0
	v_mov_b32_e32 v16, v0
	v_mov_b32_e32 v17, v0
	v_mov_b32_e32 v18, v0
	v_mov_b32_e32 v19, v0
	v_mov_b32_e32 v20, v0
	v_mov_b32_e32 v21, v0
	v_mov_b32_e32 v22, v0
	v_mov_b32_e32 v23, v0
	v_mov_b32_e32 v24, v0
	v_mov_b32_e32 v25, v0
	v_mov_b32_e32 v26, v0
	v_mov_b32_e32 v27, v0
	v_mov_b32_e32 v28, v0
	v_mov_b32_e32 v29, v0
	v_mov_b32_e32 v30, v0
	v_mov_b32_e32 v31, v0
	v_mov_b32_e32 v48, v0
	v_mov_b32_e32 v49, v0
	v_mov_b32_e32 v50, v0
	v_mov_b32_e32 v51, v0
	v_mov_b32_e32 v52, v0
	v_mov_b32_e32 v53, v0
	v_mov_b32_e32 v54, v0
	v_mov_b32_e32 v55, v0
	v_mov_b32_e32 v56, v0
	v_mov_b32_e32 v57, v0
	v_mov_b32_e32 v58, v0
	v_mov_b32_e32 v59, v0
	v_mov_b32_e32 v60, v0
	v_mov_b32_e32 v61, v0
	v_mov_b32_e32 v62, v0
	v_mov_b32_e32 v63, v0
	v_mov_b32_e32 v80, v0
	v_mov_b32_e32 v81, v0
	v_mov_b32_e32 v82, v0
	v_mov_b32_e32 v83, v0
	v_mov_b32_e32 v84, v0
	v_mov_b32_e32 v85, v0
	v_mov_b32_e32 v86, v0
	v_mov_b32_e32 v87, v0
	v_mov_b32_e32 v88, v0
	v_mov_b32_e32 v89, v0
	v_mov_b32_e32 v90, v0
	v_mov_b32_e32 v91, v0
	v_mov_b32_e32 v92, v0
	v_mov_b32_e32 v93, v0
	v_mov_b32_e32 v94, v0
	v_mov_b32_e32 v95, v0
	v_mov_b32_e32 v112, v0
	v_mov_b32_e32 v113, v0
	v_mov_b32_e32 v114, v0
	v_mov_b32_e32 v115, v0
	v_mov_b32_e32 v116, v0
	v_mov_b32_e32 v117, v0
	v_mov_b32_e32 v118, v0
	v_mov_b32_e32 v119, v0
	v_mov_b32_e32 v120, v0
	v_mov_b32_e32 v121, v0
	v_mov_b32_e32 v122, v0
	v_mov_b32_e32 v123, v0
	v_mov_b32_e32 v124, v0
	v_mov_b32_e32 v125, v0
	v_mov_b32_e32 v126, v0
	v_mov_b32_e32 v127, v0
	v_readfirstlane_b32 s92, v190
	v_readfirstlane_b32 s93, v191
	v_readfirstlane_b32 s94, v188
	v_readfirstlane_b32 s95, v189
	s_nop 1
	v_subrev_u32_e32 v248, s92, v190
	v_add_u32_e32 v249, 0x58000, v248
	v_add_u32_e32 v250, 0xb0000, v248
	v_add_u32_e32 v251, 0x108000, v248
	s_add_u32 s92, s92, 0xad00000
	s_addc_u32 s93, s93, 0
	s_add_u32 s94, s94, 0x1400000
	s_addc_u32 s95, s95, 0
	s_branch .LBB0_958

.LBB0_960:
	s_andn2_b64 vcc, exec, s[6:7]
	s_cbranch_vccnz .LBB0_963
	s_add_i32 s34, s34, 2
	s_and_b32 s6, s34, 2
	s_mul_i32 s6, s6, 0x9000
	v_add_u32_e32 v196, s6, v193
	s_cmpk_eq_i32 s2, 0x1500
	s_waitcnt vmcnt(0)
	ds_write_b128 v196, v[128:131]
	ds_write_b128 v196, v[132:135] offset:36864
	ds_write_b128 v196, v[136:139] offset:9216
	ds_write_b128 v196, v[140:143] offset:46080
	ds_write_b128 v196, v[144:147] offset:18432
	ds_write_b128 v196, v[148:151] offset:55296
	ds_write_b128 v196, v[152:155] offset:27648
	ds_write_b128 v196, v[156:159] offset:64512
	s_cbranch_scc1 .LBB0_956
	s_add_u32 s96, s92, s2
	s_addc_u32 s97, s93, s3
	s_add_u32 s98, s94, s2
	s_addc_u32 s99, s95, s3
	global_load_dwordx4 v[128:131], v248, s[96:97] offset:256
	global_load_dwordx4 v[132:135], v248, s[98:99] offset:256
	global_load_dwordx4 v[136:139], v249, s[96:97] offset:256
	global_load_dwordx4 v[140:143], v249, s[98:99] offset:256
	global_load_dwordx4 v[144:147], v250, s[96:97] offset:256
	global_load_dwordx4 v[148:151], v250, s[98:99] offset:256
	global_load_dwordx4 v[152:155], v251, s[96:97] offset:256
	global_load_dwordx4 v[156:159], v251, s[98:99] offset:256
	s_branch .LBB0_956

.LBB0_1046:
	s_and_b32 s2, s48, 7
	v_readlane_b32 s3, v253, 25
	s_or_b32 s2, s2, s3
	s_ashr_i32 s3, s48, 31
	s_lshr_b32 s3, s3, 27
	s_add_i32 s3, s48, s3
	s_lshl_b32 s6, s2, 8
	s_ashr_i32 s2, s48, 3
	s_lshl_b32 s3, s3, 6
	s_lshr_b32 s7, s2, 30
	s_and_b32 s3, s3, 0xfffff800
	s_add_i32 s7, s2, s7
	v_mov_b32_e32 v188, v234
	s_add_i32 s6, s6, s3
	s_and_b32 s7, s7, 0xfffffc
	s_sub_i32 s2, s2, s7
	v_ashrrev_i32_e32 v50, 3, v188
	v_add_u32_e32 v0, s6, v50
	s_lshl_b32 s7, s2, 8
	v_ashrrev_i32_e32 v1, 31, v0
	v_readlane_b32 s12, v252, 20
	v_and_b32_e32 v51, 7, v188
	v_lshlrev_b64 v[0:1], 11, v[0:1]
	v_add_u32_e32 v2, s7, v50
	v_readlane_b32 s13, v252, 21
	v_ashrrev_i32_e32 v3, 31, v2
	v_lshlrev_b32_e32 v192, 4, v51
	v_lshl_add_u64 v[0:1], s[12:13], 0, v[0:1]
	v_mov_b32_e32 v193, v201
	v_lshlrev_b64 v[32:33], 11, v[2:3]
	v_lshl_add_u64 v[34:35], v[0:1], 0, v[192:193]
	v_lshl_add_u64 v[2:3], s[4:5], 0, v[32:33]
	v_add_co_u32_e32 v38, vcc, s25, v34
	v_lshl_add_u64 v[36:37], v[2:3], 0, v[192:193]
	s_nop 0
	v_addc_co_u32_e32 v39, vcc, 0, v35, vcc
	v_add_co_u32_e32 v40, vcc, s25, v36
	s_mov_b32 s1, 0x40000
	s_nop 0
	v_addc_co_u32_e32 v41, vcc, 0, v37, vcc
	v_add_co_u32_e32 v42, vcc, s1, v34
	s_mov_b32 s2, 0x60000
	s_nop 0
	v_addc_co_u32_e32 v43, vcc, 0, v35, vcc
	v_add_co_u32_e32 v44, vcc, s1, v36
	global_load_dwordx4 v[0:3], v[34:35], off
	global_load_dwordx4 v[4:7], v[36:37], off
	v_addc_co_u32_e32 v45, vcc, 0, v37, vcc
	v_add_co_u32_e32 v46, vcc, s2, v34
	global_load_dwordx4 v[8:11], v[38:39], off
	global_load_dwordx4 v[12:15], v[40:41], off
	v_addc_co_u32_e32 v47, vcc, 0, v35, vcc
	v_add_co_u32_e32 v48, vcc, s2, v36
	global_load_dwordx4 v[16:19], v[42:43], off
	global_load_dwordx4 v[20:23], v[44:45], off
	v_addc_co_u32_e32 v49, vcc, 0, v37, vcc
	global_load_dwordx4 v[24:27], v[46:47], off
	global_load_dwordx4 v[28:31], v[48:49], off
	v_lshlrev_b32_e32 v194, 3, v51
	v_mul_lo_u32 v51, v50, s24
	v_add3_u32 v189, v51, v192, 0
	v_readfirstlane_b32 s12, v188
	s_ashr_i32 s17, s12, 6
	s_and_b32 s2, s47, 7
	s_lshl_b32 s13, s17, 7
	s_lshl_b32 s2, s2, 8
	v_and_b32_e32 v193, 31, v188
	s_and_b32 s22, s13, 0x80
	s_ashr_i32 s34, s12, 1
	s_andn2_b32 s34, s34, 63
	s_or_b32 s2, s2, s3
	s_add_i32 s2, s2, s15
	v_bfe_u32 v243, v188, 5, 1
	v_or_b32_e32 v32, v32, v192
	s_mov_b32 s0, 0x40000
	s_mov_b32 s1, 0x60000
	s_mov_b32 s16, 0
	v_lshlrev_b32_e32 v191, 4, v243
	v_lshl_add_u64 v[184:185], s[30:31], 0, v[32:33]
	s_mov_b32 s35, 2
	s_waitcnt vmcnt(7)
	ds_write_b128 v189, v[0:3]
	s_waitcnt vmcnt(6)
	ds_write_b128 v189, v[4:7] offset:36864
	s_waitcnt vmcnt(5)
	ds_write_b128 v189, v[8:11] offset:9216
	s_waitcnt vmcnt(4)
	ds_write_b128 v189, v[12:15] offset:46080
	s_waitcnt vmcnt(3)
	ds_write_b128 v189, v[16:19] offset:18432
	s_waitcnt vmcnt(2)
	ds_write_b128 v189, v[20:23] offset:55296
	s_waitcnt vmcnt(1)
	ds_write_b128 v189, v[24:27] offset:27648
	s_waitcnt vmcnt(0)
	ds_write_b128 v189, v[28:31] offset:64512
	s_waitcnt lgkmcnt(0)
	s_barrier
	global_load_dwordx4 v[128:131], v[34:35], off offset:128
	global_load_dwordx4 v[132:135], v[36:37], off offset:128
	global_load_dwordx4 v[136:139], v[38:39], off offset:128
	global_load_dwordx4 v[140:143], v[40:41], off offset:128
	global_load_dwordx4 v[144:147], v[42:43], off offset:128
	global_load_dwordx4 v[148:151], v[44:45], off offset:128
	global_load_dwordx4 v[152:155], v[46:47], off offset:128
	global_load_dwordx4 v[156:159], v[48:49], off offset:128
	v_or_b32_e32 v0, s22, v193
	v_mul_u32_u24_e32 v190, 0x90, v0
	v_or_b32_e32 v0, s34, v193
	v_mul_lo_u32 v195, v0, s24
	v_add_u32_e32 v0, s2, v50
	v_ashrrev_i32_e32 v1, 31, v0
	v_lshlrev_b64 v[0:1], 11, v[0:1]
	v_or_b32_e32 v0, v0, v192
	v_lshl_add_u64 v[186:187], s[10:11], 0, v[0:1]
	v_mov_b32_e32 v0, 0
	s_mov_b64 s[2:3], 0
	v_mov_b32_e32 v1, v0
	v_mov_b32_e32 v2, v0
	v_mov_b32_e32 v3, v0
	v_mov_b32_e32 v4, v0
	v_mov_b32_e32 v5, v0
	v_mov_b32_e32 v6, v0
	v_mov_b32_e32 v7, v0
	v_mov_b32_e32 v8, v0
	v_mov_b32_e32 v9, v0
	v_mov_b32_e32 v10, v0
	v_mov_b32_e32 v11, v0
	v_mov_b32_e32 v12, v0
	v_mov_b32_e32 v13, v0
	v_mov_b32_e32 v14, v0
	v_mov_b32_e32 v15, v0
	v_mov_b32_e32 v32, v0
	v_mov_b32_e32 v33, v0
	v_mov_b32_e32 v34, v0
	v_mov_b32_e32 v35, v0
	v_mov_b32_e32 v36, v0
	v_mov_b32_e32 v37, v0
	v_mov_b32_e32 v38, v0
	v_mov_b32_e32 v39, v0
	v_mov_b32_e32 v40, v0
	v_mov_b32_e32 v41, v0
	v_mov_b32_e32 v42, v0
	v_mov_b32_e32 v43, v0
	v_mov_b32_e32 v44, v0
	v_mov_b32_e32 v45, v0
	v_mov_b32_e32 v46, v0
	v_mov_b32_e32 v47, v0
	v_mov_b32_e32 v64, v0
	v_mov_b32_e32 v65, v0
	v_mov_b32_e32 v66, v0
	v_mov_b32_e32 v67, v0
	v_mov_b32_e32 v68, v0
	v_mov_b32_e32 v69, v0
	v_mov_b32_e32 v70, v0
	v_mov_b32_e32 v71, v0
	v_mov_b32_e32 v72, v0
	v_mov_b32_e32 v73, v0
	v_mov_b32_e32 v74, v0
	v_mov_b32_e32 v75, v0
	v_mov_b32_e32 v76, v0
	v_mov_b32_e32 v77, v0
	v_mov_b32_e32 v78, v0
	v_mov_b32_e32 v79, v0
	v_mov_b32_e32 v96, v0
	v_mov_b32_e32 v97, v0
	v_mov_b32_e32 v98, v0
	v_mov_b32_e32 v99, v0
	v_mov_b32_e32 v100, v0
	v_mov_b32_e32 v101, v0
	v_mov_b32_e32 v102, v0
	v_mov_b32_e32 v103, v0
	v_mov_b32_e32 v104, v0
	v_mov_b32_e32 v105, v0
	v_mov_b32_e32 v106, v0
	v_mov_b32_e32 v107, v0
	v_mov_b32_e32 v108, v0
	v_mov_b32_e32 v109, v0
	v_mov_b32_e32 v110, v0
	v_mov_b32_e32 v111, v0
	v_mov_b32_e32 v16, v0
	v_mov_b32_e32 v17, v0
	v_mov_b32_e32 v18, v0
	v_mov_b32_e32 v19, v0
	v_mov_b32_e32 v20, v0
	v_mov_b32_e32 v21, v0
	v_mov_b32_e32 v22, v0
	v_mov_b32_e32 v23, v0
	v_mov_b32_e32 v24, v0
	v_mov_b32_e32 v25, v0
	v_mov_b32_e32 v26, v0
	v_mov_b32_e32 v27, v0
	v_mov_b32_e32 v28, v0
	v_mov_b32_e32 v29, v0
	v_mov_b32_e32 v30, v0
	v_mov_b32_e32 v31, v0
	v_mov_b32_e32 v48, v0
	v_mov_b32_e32 v49, v0
	v_mov_b32_e32 v50, v0
	v_mov_b32_e32 v51, v0
	v_mov_b32_e32 v52, v0
	v_mov_b32_e32 v53, v0
	v_mov_b32_e32 v54, v0
	v_mov_b32_e32 v55, v0
	v_mov_b32_e32 v56, v0
	v_mov_b32_e32 v57, v0
	v_mov_b32_e32 v58, v0
	v_mov_b32_e32 v59, v0
	v_mov_b32_e32 v60, v0
	v_mov_b32_e32 v61, v0
	v_mov_b32_e32 v62, v0
	v_mov_b32_e32 v63, v0
	v_mov_b32_e32 v80, v0
	v_mov_b32_e32 v81, v0
	v_mov_b32_e32 v82, v0
	v_mov_b32_e32 v83, v0
	v_mov_b32_e32 v84, v0
	v_mov_b32_e32 v85, v0
	v_mov_b32_e32 v86, v0
	v_mov_b32_e32 v87, v0
	v_mov_b32_e32 v88, v0
	v_mov_b32_e32 v89, v0
	v_mov_b32_e32 v90, v0
	v_mov_b32_e32 v91, v0
	v_mov_b32_e32 v92, v0
	v_mov_b32_e32 v93, v0
	v_mov_b32_e32 v94, v0
	v_mov_b32_e32 v95, v0
	v_mov_b32_e32 v112, v0
	v_mov_b32_e32 v113, v0
	v_mov_b32_e32 v114, v0
	v_mov_b32_e32 v115, v0
	v_mov_b32_e32 v116, v0
	v_mov_b32_e32 v117, v0
	v_mov_b32_e32 v118, v0
	v_mov_b32_e32 v119, v0
	v_mov_b32_e32 v120, v0
	v_mov_b32_e32 v121, v0
	v_mov_b32_e32 v122, v0
	v_mov_b32_e32 v123, v0
	v_mov_b32_e32 v124, v0
	v_mov_b32_e32 v125, v0
	v_mov_b32_e32 v126, v0
	v_mov_b32_e32 v127, v0
	v_readfirstlane_b32 s92, v186
	v_readfirstlane_b32 s93, v187
	v_readfirstlane_b32 s94, v184
	v_readfirstlane_b32 s95, v185
	s_nop 1
	v_subrev_u32_e32 v248, s92, v186
	v_add_u32_e32 v249, 0x20000, v248
	v_add_u32_e32 v250, 0x40000, v248
	v_add_u32_e32 v251, 0x60000, v248
	s_add_u32 s92, s92, 0x6d00000
	s_addc_u32 s93, s93, 0
	s_add_u32 s94, s94, 0x1980000
	s_addc_u32 s95, s95, 0
	s_branch .LBB0_1049

.LBB0_1049:
	s_add_i32 s12, s35, -2
	s_and_b32 s12, s12, 2
	s_mul_i32 s12, s12, 0x9000
	s_add_i32 s12, s12, 0
	v_add3_u32 v200, s12, v195, v191
	ds_read_b128 v[160:163], v200 offset:36864
	v_add3_u32 v214, s12, v190, v191
	ds_read_b128 v[164:167], v214
	ds_read_b128 v[168:171], v214 offset:4608
	ds_read_b128 v[172:175], v214 offset:9216
	ds_read_b128 v[176:179], v214 offset:13824
	s_cmpk_eq_i32 s2, 0x780
	s_waitcnt lgkmcnt(3)
	v_mfma_f32_32x32x16_bf16 v[112:127], v[160:163], v[164:167], v[112:127]
	s_waitcnt lgkmcnt(2)
	v_mfma_f32_32x32x16_bf16 v[80:95], v[160:163], v[168:171], v[80:95]
	s_waitcnt lgkmcnt(1)
	v_mfma_f32_32x32x16_bf16 v[48:63], v[160:163], v[172:175], v[48:63]
	s_waitcnt lgkmcnt(0)
	v_mfma_f32_32x32x16_bf16 v[16:31], v[160:163], v[176:179], v[16:31]
	ds_read_b128 v[160:163], v200 offset:41472
	s_waitcnt lgkmcnt(0)
	v_mfma_f32_32x32x16_bf16 v[96:111], v[160:163], v[164:167], v[96:111]
	v_mfma_f32_32x32x16_bf16 v[64:79], v[160:163], v[168:171], v[64:79]
	v_mfma_f32_32x32x16_bf16 v[32:47], v[160:163], v[172:175], v[32:47]
	ds_read_b128 v[164:167], v200 offset:36896
	ds_read_b128 v[168:171], v214 offset:32
	ds_read_b128 v[172:175], v214 offset:4640
	ds_read_b128 v[180:183], v214 offset:9248
	ds_read_b128 v[196:199], v214 offset:13856
	ds_read_b128 v[202:205], v200 offset:41504
	v_mfma_f32_32x32x16_bf16 v[0:15], v[160:163], v[176:179], v[0:15]
	s_waitcnt lgkmcnt(4)
	v_mfma_f32_32x32x16_bf16 v[112:127], v[164:167], v[168:171], v[112:127]
	s_waitcnt lgkmcnt(3)
	v_mfma_f32_32x32x16_bf16 v[80:95], v[164:167], v[172:175], v[80:95]
	s_waitcnt lgkmcnt(2)
	v_mfma_f32_32x32x16_bf16 v[48:63], v[164:167], v[180:183], v[48:63]
	s_waitcnt lgkmcnt(1)
	v_mfma_f32_32x32x16_bf16 v[16:31], v[164:167], v[196:199], v[16:31]
	s_waitcnt lgkmcnt(0)
	v_mfma_f32_32x32x16_bf16 v[96:111], v[202:205], v[168:171], v[96:111]
	v_mfma_f32_32x32x16_bf16 v[64:79], v[202:205], v[172:175], v[64:79]
	ds_read_b128 v[160:163], v200 offset:36928
	ds_read_b128 v[206:209], v200 offset:41536
	ds_read_b128 v[164:167], v214 offset:64
	ds_read_b128 v[168:171], v214 offset:4672
	ds_read_b128 v[172:175], v214 offset:9280
	ds_read_b128 v[210:213], v214 offset:13888
	v_mfma_f32_32x32x16_bf16 v[32:47], v[202:205], v[180:183], v[32:47]
	v_mfma_f32_32x32x16_bf16 v[0:15], v[202:205], v[196:199], v[0:15]
	s_waitcnt lgkmcnt(3)
	v_mfma_f32_32x32x16_bf16 v[112:127], v[160:163], v[164:167], v[112:127]
	s_waitcnt lgkmcnt(2)
	v_mfma_f32_32x32x16_bf16 v[80:95], v[160:163], v[168:171], v[80:95]
	s_waitcnt lgkmcnt(1)
	v_mfma_f32_32x32x16_bf16 v[48:63], v[160:163], v[172:175], v[48:63]
	s_waitcnt lgkmcnt(0)
	v_mfma_f32_32x32x16_bf16 v[16:31], v[160:163], v[210:213], v[16:31]
	v_mfma_f32_32x32x16_bf16 v[96:111], v[206:209], v[164:167], v[96:111]
	v_mfma_f32_32x32x16_bf16 v[64:79], v[206:209], v[168:171], v[64:79]
	v_mfma_f32_32x32x16_bf16 v[32:47], v[206:209], v[172:175], v[32:47]
	ds_read_b128 v[176:179], v200 offset:36960
	ds_read_b128 v[160:163], v200 offset:41568
	ds_read_b128 v[180:183], v214 offset:96
	ds_read_b128 v[172:175], v214 offset:4704
	ds_read_b128 v[168:171], v214 offset:9312
	ds_read_b128 v[164:167], v214 offset:13920
	v_mfma_f32_32x32x16_bf16 v[0:15], v[206:209], v[210:213], v[0:15]
	s_cbranch_scc1 .LBB0_1048
	s_and_b32 s12, s35, 2
	s_mul_i32 s12, s12, 0x9000
	v_add_u32_e32 v196, s12, v189
	s_cmp_gt_u32 s16, 13
	s_waitcnt vmcnt(7)
	ds_write_b128 v196, v[128:131]
	s_waitcnt vmcnt(6)
	ds_write_b128 v196, v[132:135] offset:36864
	s_waitcnt vmcnt(5)
	ds_write_b128 v196, v[136:139] offset:9216
	s_waitcnt vmcnt(4)
	ds_write_b128 v196, v[140:143] offset:46080
	s_waitcnt vmcnt(3)
	ds_write_b128 v196, v[144:147] offset:18432
	s_waitcnt vmcnt(2)
	ds_write_b128 v196, v[148:151] offset:55296
	s_waitcnt vmcnt(1)
	ds_write_b128 v196, v[152:155] offset:27648
	s_waitcnt vmcnt(0)
	ds_write_b128 v196, v[156:159] offset:64512
	s_cbranch_scc1 .LBB0_1047
	s_add_u32 s96, s92, s2
	s_addc_u32 s97, s93, s3
	s_add_u32 s98, s94, s2
	s_addc_u32 s99, s95, s3
	global_load_dwordx4 v[128:131], v248, s[96:97] offset:256
	global_load_dwordx4 v[132:135], v248, s[98:99] offset:256
	global_load_dwordx4 v[136:139], v249, s[96:97] offset:256
	global_load_dwordx4 v[140:143], v249, s[98:99] offset:256
	global_load_dwordx4 v[144:147], v250, s[96:97] offset:256
	global_load_dwordx4 v[148:151], v250, s[98:99] offset:256
	global_load_dwordx4 v[152:155], v251, s[96:97] offset:256
	global_load_dwordx4 v[156:159], v251, s[98:99] offset:256
	s_branch .LBB0_1047
